# conv LayerNorm 16-lane reductions via DPP moves instead of ds_bpermute
# speedup vs baseline: 1.0383x; 1.0013x over previous
; DI void conv_item(LAS unsigned char* lds, int item, const bf16_t* P, const float* cw, const float* cb, const float* lng, const float* lnb, bf16_t* MIX) {
;     ...
;     const int c = tid & 127, tq = tid >> 7;
;     float y[32];
;     {
;         float w[31];
; #pragma unroll
;         for (int k = 0; k < 31; ++k) w[k] = cw[k * 1024 + cbase + c];
;         const float bias = cb[cbase + c];
; #pragma unroll
;         for (int i = 0; i < 32; ++i) y[i] = bias;
;         float uw[62];
; #pragma unroll
;         for (int j = 0; j < 62; ++j) uw[j] = U[(tq * 32 + j) * 128 + c];
; #pragma unroll
;         for (int i = 0; i < 32; ++i)
; #pragma unroll
;             for (int k = 0; k < 31; ++k) y[i] += w[k] * uw[i + k];
.LBB0_517:
	s_or_b64 exec, exec, s[26:27]
	s_lshl_b32 s12, s37, 2
	v_lshrrev_b32_e32 v251, 6, v253
	v_lshlrev_b32_e32 v251, 13, v251
	v_lshl_add_u32 v251, v252, 3, v251
	s_waitcnt lgkmcnt(0)
	s_barrier
	ds_read_b64 v[222:223], v251
	ds_read_b64 v[224:225], v251 offset:512
	ds_read_b64 v[226:227], v251 offset:1024
	ds_read_b64 v[228:229], v251 offset:1536
	ds_read_b64 v[230:231], v251 offset:2048
	ds_read_b64 v[232:233], v251 offset:2560
	ds_read_b64 v[234:235], v251 offset:3072
	ds_read_b64 v[236:237], v251 offset:3584
	ds_read_b64 v[238:239], v251 offset:4096
	ds_read_b64 v[240:241], v251 offset:4608
	ds_read_b64 v[242:243], v251 offset:5120
	ds_read_b64 v[244:245], v251 offset:5632
	ds_read_b64 v[246:247], v251 offset:6144
	ds_read_b64 v[248:249], v251 offset:6656
	ds_read_b64 v[8:9], v251 offset:7168
	ds_read_b64 v[10:11], v251 offset:7680
	ds_read_b64 v[12:13], v251 offset:8192
	ds_read_b64 v[14:15], v251 offset:8704
	ds_read_b64 v[16:17], v251 offset:9216
	ds_read_b64 v[18:19], v251 offset:9728
	ds_read_b64 v[20:21], v251 offset:10240
	ds_read_b64 v[22:23], v251 offset:10752
	ds_read_b64 v[28:29], v251 offset:11264
	ds_read_b64 v[30:31], v251 offset:11776
	ds_read_b64 v[32:33], v251 offset:12288
	ds_read_b64 v[34:35], v251 offset:12800
	ds_read_b64 v[36:37], v251 offset:13312
	ds_read_b64 v[38:39], v251 offset:13824
	ds_read_b64 v[50:51], v251 offset:14336
	ds_read_b64 v[52:53], v251 offset:14848
	ds_read_b64 v[54:55], v251 offset:15360
	ds_read_b64 v[56:57], v251 offset:15872
	ds_read_b64 v[58:59], v251 offset:16384
	ds_read_b64 v[60:61], v251 offset:16896
	ds_read_b64 v[62:63], v251 offset:17408
	ds_read_b64 v[64:65], v251 offset:17920
	ds_read_b64 v[66:67], v251 offset:18432
	ds_read_b64 v[92:93], v251 offset:18944
	ds_read_b64 v[94:95], v251 offset:19456
	ds_read_b64 v[96:97], v251 offset:19968
	ds_read_b64 v[98:99], v251 offset:20480
	ds_read_b64 v[100:101], v251 offset:20992
	ds_read_b64 v[102:103], v251 offset:21504
	ds_read_b64 v[104:105], v251 offset:22016
	ds_read_b64 v[106:107], v251 offset:22528
	ds_read_b64 v[108:109], v251 offset:23040
	s_waitcnt vmcnt(0) lgkmcnt(0)
	s_barrier
	v_pk_fma_f32 v[190:191], v[126:127], v[222:223], v[188:189]
	v_pk_fma_f32 v[190:191], v[128:129], v[224:225], v[190:191]
	v_pk_fma_f32 v[192:193], v[126:127], v[224:225], v[188:189]
	v_pk_fma_f32 v[190:191], v[130:131], v[226:227], v[190:191]
	v_pk_fma_f32 v[192:193], v[128:129], v[226:227], v[192:193]
	v_pk_fma_f32 v[194:195], v[126:127], v[226:227], v[188:189]
	v_pk_fma_f32 v[190:191], v[132:133], v[228:229], v[190:191]
	v_pk_fma_f32 v[192:193], v[130:131], v[228:229], v[192:193]
	v_pk_fma_f32 v[194:195], v[128:129], v[228:229], v[194:195]
	v_pk_fma_f32 v[196:197], v[126:127], v[228:229], v[188:189]
	v_pk_fma_f32 v[190:191], v[134:135], v[230:231], v[190:191]
	v_pk_fma_f32 v[192:193], v[132:133], v[230:231], v[192:193]
	v_pk_fma_f32 v[194:195], v[130:131], v[230:231], v[194:195]
	v_pk_fma_f32 v[196:197], v[128:129], v[230:231], v[196:197]
	v_pk_fma_f32 v[198:199], v[126:127], v[230:231], v[188:189]
	v_pk_fma_f32 v[190:191], v[136:137], v[232:233], v[190:191]
	v_pk_fma_f32 v[192:193], v[134:135], v[232:233], v[192:193]
	v_pk_fma_f32 v[194:195], v[132:133], v[232:233], v[194:195]
	v_pk_fma_f32 v[196:197], v[130:131], v[232:233], v[196:197]
	v_pk_fma_f32 v[198:199], v[128:129], v[232:233], v[198:199]
	v_pk_fma_f32 v[200:201], v[126:127], v[232:233], v[188:189]
	v_pk_fma_f32 v[190:191], v[138:139], v[234:235], v[190:191]
	v_pk_fma_f32 v[192:193], v[136:137], v[234:235], v[192:193]
	v_pk_fma_f32 v[194:195], v[134:135], v[234:235], v[194:195]
	v_pk_fma_f32 v[196:197], v[132:133], v[234:235], v[196:197]
	v_pk_fma_f32 v[198:199], v[130:131], v[234:235], v[198:199]
	v_pk_fma_f32 v[200:201], v[128:129], v[234:235], v[200:201]
	v_pk_fma_f32 v[202:203], v[126:127], v[234:235], v[188:189]
	v_pk_fma_f32 v[190:191], v[140:141], v[236:237], v[190:191]
	v_pk_fma_f32 v[192:193], v[138:139], v[236:237], v[192:193]
	v_pk_fma_f32 v[194:195], v[136:137], v[236:237], v[194:195]
	v_pk_fma_f32 v[196:197], v[134:135], v[236:237], v[196:197]
	v_pk_fma_f32 v[198:199], v[132:133], v[236:237], v[198:199]
	v_pk_fma_f32 v[200:201], v[130:131], v[236:237], v[200:201]
	v_pk_fma_f32 v[202:203], v[128:129], v[236:237], v[202:203]
	v_pk_fma_f32 v[204:205], v[126:127], v[236:237], v[188:189]
	v_pk_fma_f32 v[190:191], v[142:143], v[238:239], v[190:191]
	v_pk_fma_f32 v[192:193], v[140:141], v[238:239], v[192:193]
	v_pk_fma_f32 v[194:195], v[138:139], v[238:239], v[194:195]
	v_pk_fma_f32 v[196:197], v[136:137], v[238:239], v[196:197]
	v_pk_fma_f32 v[198:199], v[134:135], v[238:239], v[198:199]
	v_pk_fma_f32 v[200:201], v[132:133], v[238:239], v[200:201]
	v_pk_fma_f32 v[202:203], v[130:131], v[238:239], v[202:203]
	v_pk_fma_f32 v[204:205], v[128:129], v[238:239], v[204:205]
	v_pk_fma_f32 v[206:207], v[126:127], v[238:239], v[188:189]
	v_pk_fma_f32 v[190:191], v[144:145], v[240:241], v[190:191]
	v_pk_fma_f32 v[192:193], v[142:143], v[240:241], v[192:193]
	v_pk_fma_f32 v[194:195], v[140:141], v[240:241], v[194:195]
	v_pk_fma_f32 v[196:197], v[138:139], v[240:241], v[196:197]
	v_pk_fma_f32 v[198:199], v[136:137], v[240:241], v[198:199]
	v_pk_fma_f32 v[200:201], v[134:135], v[240:241], v[200:201]
	v_pk_fma_f32 v[202:203], v[132:133], v[240:241], v[202:203]
	v_pk_fma_f32 v[204:205], v[130:131], v[240:241], v[204:205]
	v_pk_fma_f32 v[206:207], v[128:129], v[240:241], v[206:207]
	v_pk_fma_f32 v[208:209], v[126:127], v[240:241], v[188:189]
	v_pk_fma_f32 v[190:191], v[146:147], v[242:243], v[190:191]
	v_pk_fma_f32 v[192:193], v[144:145], v[242:243], v[192:193]
; DI void conv_item(LAS unsigned char* lds, int item, const bf16_t* P, const float* cw, const float* cb, const float* lng, const float* lnb, bf16_t* MIX) {
;     ...
;         for (int i = 0; i < 32; ++i)
; #pragma unroll
;             for (int k = 0; k < 31; ++k) y[i] += w[k] * uw[i + k];
	v_pk_fma_f32 v[194:195], v[142:143], v[242:243], v[194:195]
	v_pk_fma_f32 v[196:197], v[140:141], v[242:243], v[196:197]
	v_pk_fma_f32 v[198:199], v[138:139], v[242:243], v[198:199]
	v_pk_fma_f32 v[200:201], v[136:137], v[242:243], v[200:201]
	v_pk_fma_f32 v[202:203], v[134:135], v[242:243], v[202:203]
	v_pk_fma_f32 v[204:205], v[132:133], v[242:243], v[204:205]
	v_pk_fma_f32 v[206:207], v[130:131], v[242:243], v[206:207]
	v_pk_fma_f32 v[208:209], v[128:129], v[242:243], v[208:209]
	v_pk_fma_f32 v[210:211], v[126:127], v[242:243], v[188:189]
	v_pk_fma_f32 v[190:191], v[148:149], v[244:245], v[190:191]
	v_pk_fma_f32 v[192:193], v[146:147], v[244:245], v[192:193]
	v_pk_fma_f32 v[194:195], v[144:145], v[244:245], v[194:195]
	v_pk_fma_f32 v[196:197], v[142:143], v[244:245], v[196:197]
	v_pk_fma_f32 v[198:199], v[140:141], v[244:245], v[198:199]
	v_pk_fma_f32 v[200:201], v[138:139], v[244:245], v[200:201]
	v_pk_fma_f32 v[202:203], v[136:137], v[244:245], v[202:203]
	v_pk_fma_f32 v[204:205], v[134:135], v[244:245], v[204:205]
	v_pk_fma_f32 v[206:207], v[132:133], v[244:245], v[206:207]
	v_pk_fma_f32 v[208:209], v[130:131], v[244:245], v[208:209]
	v_pk_fma_f32 v[210:211], v[128:129], v[244:245], v[210:211]
	v_pk_fma_f32 v[212:213], v[126:127], v[244:245], v[188:189]
	v_pk_fma_f32 v[190:191], v[150:151], v[246:247], v[190:191]
	v_pk_fma_f32 v[192:193], v[148:149], v[246:247], v[192:193]
	v_pk_fma_f32 v[194:195], v[146:147], v[246:247], v[194:195]
	v_pk_fma_f32 v[196:197], v[144:145], v[246:247], v[196:197]
	v_pk_fma_f32 v[198:199], v[142:143], v[246:247], v[198:199]
	v_pk_fma_f32 v[200:201], v[140:141], v[246:247], v[200:201]
	v_pk_fma_f32 v[202:203], v[138:139], v[246:247], v[202:203]
	v_pk_fma_f32 v[204:205], v[136:137], v[246:247], v[204:205]
	v_pk_fma_f32 v[206:207], v[134:135], v[246:247], v[206:207]
	v_pk_fma_f32 v[208:209], v[132:133], v[246:247], v[208:209]
	v_pk_fma_f32 v[210:211], v[130:131], v[246:247], v[210:211]
	v_pk_fma_f32 v[212:213], v[128:129], v[246:247], v[212:213]
	v_pk_fma_f32 v[214:215], v[126:127], v[246:247], v[188:189]
	v_pk_fma_f32 v[190:191], v[152:153], v[248:249], v[190:191]
	v_pk_fma_f32 v[192:193], v[150:151], v[248:249], v[192:193]
	v_pk_fma_f32 v[194:195], v[148:149], v[248:249], v[194:195]
	v_pk_fma_f32 v[196:197], v[146:147], v[248:249], v[196:197]
	v_pk_fma_f32 v[198:199], v[144:145], v[248:249], v[198:199]
	v_pk_fma_f32 v[200:201], v[142:143], v[248:249], v[200:201]
	v_pk_fma_f32 v[202:203], v[140:141], v[248:249], v[202:203]
	v_pk_fma_f32 v[204:205], v[138:139], v[248:249], v[204:205]
	v_pk_fma_f32 v[206:207], v[136:137], v[248:249], v[206:207]
	v_pk_fma_f32 v[208:209], v[134:135], v[248:249], v[208:209]
	v_pk_fma_f32 v[210:211], v[132:133], v[248:249], v[210:211]
	v_pk_fma_f32 v[212:213], v[130:131], v[248:249], v[212:213]
	v_pk_fma_f32 v[214:215], v[128:129], v[248:249], v[214:215]
	v_pk_fma_f32 v[216:217], v[126:127], v[248:249], v[188:189]
	v_pk_fma_f32 v[190:191], v[154:155], v[8:9], v[190:191]
	v_pk_fma_f32 v[192:193], v[152:153], v[8:9], v[192:193]
	v_pk_fma_f32 v[194:195], v[150:151], v[8:9], v[194:195]
	v_pk_fma_f32 v[196:197], v[148:149], v[8:9], v[196:197]
	v_pk_fma_f32 v[198:199], v[146:147], v[8:9], v[198:199]
	v_pk_fma_f32 v[200:201], v[144:145], v[8:9], v[200:201]
	v_pk_fma_f32 v[202:203], v[142:143], v[8:9], v[202:203]
	v_pk_fma_f32 v[204:205], v[140:141], v[8:9], v[204:205]
	v_pk_fma_f32 v[206:207], v[138:139], v[8:9], v[206:207]
	v_pk_fma_f32 v[208:209], v[136:137], v[8:9], v[208:209]
	v_pk_fma_f32 v[210:211], v[134:135], v[8:9], v[210:211]
	v_pk_fma_f32 v[212:213], v[132:133], v[8:9], v[212:213]
	v_pk_fma_f32 v[214:215], v[130:131], v[8:9], v[214:215]
	v_pk_fma_f32 v[216:217], v[128:129], v[8:9], v[216:217]
	v_pk_fma_f32 v[218:219], v[126:127], v[8:9], v[188:189]
	v_pk_fma_f32 v[190:191], v[156:157], v[10:11], v[190:191]
	v_pk_fma_f32 v[192:193], v[154:155], v[10:11], v[192:193]
	v_pk_fma_f32 v[194:195], v[152:153], v[10:11], v[194:195]
	v_pk_fma_f32 v[196:197], v[150:151], v[10:11], v[196:197]
	v_pk_fma_f32 v[198:199], v[148:149], v[10:11], v[198:199]
	v_pk_fma_f32 v[200:201], v[146:147], v[10:11], v[200:201]
	v_pk_fma_f32 v[202:203], v[144:145], v[10:11], v[202:203]
	v_pk_fma_f32 v[204:205], v[142:143], v[10:11], v[204:205]
	v_pk_fma_f32 v[206:207], v[140:141], v[10:11], v[206:207]
	v_pk_fma_f32 v[208:209], v[138:139], v[10:11], v[208:209]
	v_pk_fma_f32 v[210:211], v[136:137], v[10:11], v[210:211]
	v_pk_fma_f32 v[212:213], v[134:135], v[10:11], v[212:213]
	v_pk_fma_f32 v[214:215], v[132:133], v[10:11], v[214:215]
	v_pk_fma_f32 v[216:217], v[130:131], v[10:11], v[216:217]
	v_pk_fma_f32 v[218:219], v[128:129], v[10:11], v[218:219]
	v_pk_fma_f32 v[220:221], v[126:127], v[10:11], v[188:189]
	v_pk_fma_f32 v[190:191], v[158:159], v[12:13], v[190:191]
	v_pk_fma_f32 v[192:193], v[156:157], v[12:13], v[192:193]
	v_pk_fma_f32 v[194:195], v[154:155], v[12:13], v[194:195]
	v_pk_fma_f32 v[196:197], v[152:153], v[12:13], v[196:197]
	v_pk_fma_f32 v[198:199], v[150:151], v[12:13], v[198:199]
	v_pk_fma_f32 v[200:201], v[148:149], v[12:13], v[200:201]
	v_pk_fma_f32 v[202:203], v[146:147], v[12:13], v[202:203]
	v_pk_fma_f32 v[204:205], v[144:145], v[12:13], v[204:205]
	v_pk_fma_f32 v[206:207], v[142:143], v[12:13], v[206:207]
	v_pk_fma_f32 v[208:209], v[140:141], v[12:13], v[208:209]
	v_pk_fma_f32 v[210:211], v[138:139], v[12:13], v[210:211]
	v_pk_fma_f32 v[212:213], v[136:137], v[12:13], v[212:213]
	v_pk_fma_f32 v[214:215], v[134:135], v[12:13], v[214:215]
	v_pk_fma_f32 v[216:217], v[132:133], v[12:13], v[216:217]
	v_pk_fma_f32 v[218:219], v[130:131], v[12:13], v[218:219]
; DI void conv_item(LAS unsigned char* lds, int item, const bf16_t* P, const float* cw, const float* cb, const float* lng, const float* lnb, bf16_t* MIX) {
;     ...
;         for (int i = 0; i < 32; ++i)
; #pragma unroll
;             for (int k = 0; k < 31; ++k) y[i] += w[k] * uw[i + k];
	v_pk_fma_f32 v[220:221], v[128:129], v[12:13], v[220:221]
	v_pk_fma_f32 v[190:191], v[160:161], v[14:15], v[190:191]
	v_pk_fma_f32 v[192:193], v[158:159], v[14:15], v[192:193]
	v_pk_fma_f32 v[194:195], v[156:157], v[14:15], v[194:195]
	v_pk_fma_f32 v[196:197], v[154:155], v[14:15], v[196:197]
	v_pk_fma_f32 v[198:199], v[152:153], v[14:15], v[198:199]
	v_pk_fma_f32 v[200:201], v[150:151], v[14:15], v[200:201]
	v_pk_fma_f32 v[202:203], v[148:149], v[14:15], v[202:203]
	v_pk_fma_f32 v[204:205], v[146:147], v[14:15], v[204:205]
	v_pk_fma_f32 v[206:207], v[144:145], v[14:15], v[206:207]
	v_pk_fma_f32 v[208:209], v[142:143], v[14:15], v[208:209]
	v_pk_fma_f32 v[210:211], v[140:141], v[14:15], v[210:211]
	v_pk_fma_f32 v[212:213], v[138:139], v[14:15], v[212:213]
	v_pk_fma_f32 v[214:215], v[136:137], v[14:15], v[214:215]
	v_pk_fma_f32 v[216:217], v[134:135], v[14:15], v[216:217]
	v_pk_fma_f32 v[218:219], v[132:133], v[14:15], v[218:219]
	v_pk_fma_f32 v[220:221], v[130:131], v[14:15], v[220:221]
	v_pk_fma_f32 v[190:191], v[162:163], v[16:17], v[190:191]
	v_pk_fma_f32 v[192:193], v[160:161], v[16:17], v[192:193]
	v_pk_fma_f32 v[194:195], v[158:159], v[16:17], v[194:195]
	v_pk_fma_f32 v[196:197], v[156:157], v[16:17], v[196:197]
	v_pk_fma_f32 v[198:199], v[154:155], v[16:17], v[198:199]
	v_pk_fma_f32 v[200:201], v[152:153], v[16:17], v[200:201]
	v_pk_fma_f32 v[202:203], v[150:151], v[16:17], v[202:203]
	v_pk_fma_f32 v[204:205], v[148:149], v[16:17], v[204:205]
	v_pk_fma_f32 v[206:207], v[146:147], v[16:17], v[206:207]
	v_pk_fma_f32 v[208:209], v[144:145], v[16:17], v[208:209]
	v_pk_fma_f32 v[210:211], v[142:143], v[16:17], v[210:211]
	v_pk_fma_f32 v[212:213], v[140:141], v[16:17], v[212:213]
	v_pk_fma_f32 v[214:215], v[138:139], v[16:17], v[214:215]
	v_pk_fma_f32 v[216:217], v[136:137], v[16:17], v[216:217]
	v_pk_fma_f32 v[218:219], v[134:135], v[16:17], v[218:219]
	v_pk_fma_f32 v[220:221], v[132:133], v[16:17], v[220:221]
	v_pk_fma_f32 v[190:191], v[164:165], v[18:19], v[190:191]
	v_pk_fma_f32 v[192:193], v[162:163], v[18:19], v[192:193]
	v_pk_fma_f32 v[194:195], v[160:161], v[18:19], v[194:195]
	v_pk_fma_f32 v[196:197], v[158:159], v[18:19], v[196:197]
	v_pk_fma_f32 v[198:199], v[156:157], v[18:19], v[198:199]
	v_pk_fma_f32 v[200:201], v[154:155], v[18:19], v[200:201]
	v_pk_fma_f32 v[202:203], v[152:153], v[18:19], v[202:203]
	v_pk_fma_f32 v[204:205], v[150:151], v[18:19], v[204:205]
	v_pk_fma_f32 v[206:207], v[148:149], v[18:19], v[206:207]
	v_pk_fma_f32 v[208:209], v[146:147], v[18:19], v[208:209]
	v_pk_fma_f32 v[210:211], v[144:145], v[18:19], v[210:211]
	v_pk_fma_f32 v[212:213], v[142:143], v[18:19], v[212:213]
	v_pk_fma_f32 v[214:215], v[140:141], v[18:19], v[214:215]
	v_pk_fma_f32 v[216:217], v[138:139], v[18:19], v[216:217]
	v_pk_fma_f32 v[218:219], v[136:137], v[18:19], v[218:219]
	v_pk_fma_f32 v[220:221], v[134:135], v[18:19], v[220:221]
	v_pk_fma_f32 v[190:191], v[166:167], v[20:21], v[190:191]
	v_pk_fma_f32 v[192:193], v[164:165], v[20:21], v[192:193]
	v_pk_fma_f32 v[194:195], v[162:163], v[20:21], v[194:195]
	v_pk_fma_f32 v[196:197], v[160:161], v[20:21], v[196:197]
	v_pk_fma_f32 v[198:199], v[158:159], v[20:21], v[198:199]
	v_pk_fma_f32 v[200:201], v[156:157], v[20:21], v[200:201]
	v_pk_fma_f32 v[202:203], v[154:155], v[20:21], v[202:203]
	v_pk_fma_f32 v[204:205], v[152:153], v[20:21], v[204:205]
	v_pk_fma_f32 v[206:207], v[150:151], v[20:21], v[206:207]
	v_pk_fma_f32 v[208:209], v[148:149], v[20:21], v[208:209]
	v_pk_fma_f32 v[210:211], v[146:147], v[20:21], v[210:211]
	v_pk_fma_f32 v[212:213], v[144:145], v[20:21], v[212:213]
	v_pk_fma_f32 v[214:215], v[142:143], v[20:21], v[214:215]
	v_pk_fma_f32 v[216:217], v[140:141], v[20:21], v[216:217]
	v_pk_fma_f32 v[218:219], v[138:139], v[20:21], v[218:219]
	v_pk_fma_f32 v[220:221], v[136:137], v[20:21], v[220:221]
	v_pk_fma_f32 v[190:191], v[168:169], v[22:23], v[190:191]
	v_pk_fma_f32 v[192:193], v[166:167], v[22:23], v[192:193]
	v_pk_fma_f32 v[194:195], v[164:165], v[22:23], v[194:195]
	v_pk_fma_f32 v[196:197], v[162:163], v[22:23], v[196:197]
	v_pk_fma_f32 v[198:199], v[160:161], v[22:23], v[198:199]
	v_pk_fma_f32 v[200:201], v[158:159], v[22:23], v[200:201]
	v_pk_fma_f32 v[202:203], v[156:157], v[22:23], v[202:203]
	v_pk_fma_f32 v[204:205], v[154:155], v[22:23], v[204:205]
	v_pk_fma_f32 v[206:207], v[152:153], v[22:23], v[206:207]
	v_pk_fma_f32 v[208:209], v[150:151], v[22:23], v[208:209]
	v_pk_fma_f32 v[210:211], v[148:149], v[22:23], v[210:211]
	v_pk_fma_f32 v[212:213], v[146:147], v[22:23], v[212:213]
	v_pk_fma_f32 v[214:215], v[144:145], v[22:23], v[214:215]
	v_pk_fma_f32 v[216:217], v[142:143], v[22:23], v[216:217]
	v_pk_fma_f32 v[218:219], v[140:141], v[22:23], v[218:219]
	v_pk_fma_f32 v[220:221], v[138:139], v[22:23], v[220:221]
	v_pk_fma_f32 v[190:191], v[170:171], v[28:29], v[190:191]
	v_pk_fma_f32 v[192:193], v[168:169], v[28:29], v[192:193]
	v_pk_fma_f32 v[194:195], v[166:167], v[28:29], v[194:195]
	v_pk_fma_f32 v[196:197], v[164:165], v[28:29], v[196:197]
	v_pk_fma_f32 v[198:199], v[162:163], v[28:29], v[198:199]
	v_pk_fma_f32 v[200:201], v[160:161], v[28:29], v[200:201]
	v_pk_fma_f32 v[202:203], v[158:159], v[28:29], v[202:203]
	v_pk_fma_f32 v[204:205], v[156:157], v[28:29], v[204:205]
	v_pk_fma_f32 v[206:207], v[154:155], v[28:29], v[206:207]
	v_pk_fma_f32 v[208:209], v[152:153], v[28:29], v[208:209]
	v_pk_fma_f32 v[210:211], v[150:151], v[28:29], v[210:211]
	v_pk_fma_f32 v[212:213], v[148:149], v[28:29], v[212:213]
	v_pk_fma_f32 v[214:215], v[146:147], v[28:29], v[214:215]
	v_pk_fma_f32 v[216:217], v[144:145], v[28:29], v[216:217]
	v_pk_fma_f32 v[218:219], v[142:143], v[28:29], v[218:219]
; DI void conv_item(LAS unsigned char* lds, int item, const bf16_t* P, const float* cw, const float* cb, const float* lng, const float* lnb, bf16_t* MIX) {
;     ...
;         for (int i = 0; i < 32; ++i)
; #pragma unroll
;             for (int k = 0; k < 31; ++k) y[i] += w[k] * uw[i + k];
	v_pk_fma_f32 v[220:221], v[140:141], v[28:29], v[220:221]
	v_pk_fma_f32 v[190:191], v[172:173], v[30:31], v[190:191]
	v_pk_fma_f32 v[192:193], v[170:171], v[30:31], v[192:193]
	v_pk_fma_f32 v[194:195], v[168:169], v[30:31], v[194:195]
	v_pk_fma_f32 v[196:197], v[166:167], v[30:31], v[196:197]
	v_pk_fma_f32 v[198:199], v[164:165], v[30:31], v[198:199]
	v_pk_fma_f32 v[200:201], v[162:163], v[30:31], v[200:201]
	v_pk_fma_f32 v[202:203], v[160:161], v[30:31], v[202:203]
	v_pk_fma_f32 v[204:205], v[158:159], v[30:31], v[204:205]
	v_pk_fma_f32 v[206:207], v[156:157], v[30:31], v[206:207]
	v_pk_fma_f32 v[208:209], v[154:155], v[30:31], v[208:209]
	v_pk_fma_f32 v[210:211], v[152:153], v[30:31], v[210:211]
	v_pk_fma_f32 v[212:213], v[150:151], v[30:31], v[212:213]
	v_pk_fma_f32 v[214:215], v[148:149], v[30:31], v[214:215]
	v_pk_fma_f32 v[216:217], v[146:147], v[30:31], v[216:217]
	v_pk_fma_f32 v[218:219], v[144:145], v[30:31], v[218:219]
	v_pk_fma_f32 v[220:221], v[142:143], v[30:31], v[220:221]
	v_pk_fma_f32 v[190:191], v[174:175], v[32:33], v[190:191]
	v_pk_fma_f32 v[192:193], v[172:173], v[32:33], v[192:193]
	v_pk_fma_f32 v[194:195], v[170:171], v[32:33], v[194:195]
	v_pk_fma_f32 v[196:197], v[168:169], v[32:33], v[196:197]
	v_pk_fma_f32 v[198:199], v[166:167], v[32:33], v[198:199]
	v_pk_fma_f32 v[200:201], v[164:165], v[32:33], v[200:201]
	v_pk_fma_f32 v[202:203], v[162:163], v[32:33], v[202:203]
	v_pk_fma_f32 v[204:205], v[160:161], v[32:33], v[204:205]
	v_pk_fma_f32 v[206:207], v[158:159], v[32:33], v[206:207]
	v_pk_fma_f32 v[208:209], v[156:157], v[32:33], v[208:209]
	v_pk_fma_f32 v[210:211], v[154:155], v[32:33], v[210:211]
	v_pk_fma_f32 v[212:213], v[152:153], v[32:33], v[212:213]
	v_pk_fma_f32 v[214:215], v[150:151], v[32:33], v[214:215]
	v_pk_fma_f32 v[216:217], v[148:149], v[32:33], v[216:217]
	v_pk_fma_f32 v[218:219], v[146:147], v[32:33], v[218:219]
	v_pk_fma_f32 v[220:221], v[144:145], v[32:33], v[220:221]
	v_pk_fma_f32 v[190:191], v[176:177], v[34:35], v[190:191]
	v_pk_fma_f32 v[192:193], v[174:175], v[34:35], v[192:193]
	v_pk_fma_f32 v[194:195], v[172:173], v[34:35], v[194:195]
	v_pk_fma_f32 v[196:197], v[170:171], v[34:35], v[196:197]
	v_pk_fma_f32 v[198:199], v[168:169], v[34:35], v[198:199]
	v_pk_fma_f32 v[200:201], v[166:167], v[34:35], v[200:201]
	v_pk_fma_f32 v[202:203], v[164:165], v[34:35], v[202:203]
	v_pk_fma_f32 v[204:205], v[162:163], v[34:35], v[204:205]
	v_pk_fma_f32 v[206:207], v[160:161], v[34:35], v[206:207]
	v_pk_fma_f32 v[208:209], v[158:159], v[34:35], v[208:209]
	v_pk_fma_f32 v[210:211], v[156:157], v[34:35], v[210:211]
	v_pk_fma_f32 v[212:213], v[154:155], v[34:35], v[212:213]
	v_pk_fma_f32 v[214:215], v[152:153], v[34:35], v[214:215]
	v_pk_fma_f32 v[216:217], v[150:151], v[34:35], v[216:217]
	v_pk_fma_f32 v[218:219], v[148:149], v[34:35], v[218:219]
	v_pk_fma_f32 v[220:221], v[146:147], v[34:35], v[220:221]
	v_pk_fma_f32 v[190:191], v[178:179], v[36:37], v[190:191]
	v_pk_fma_f32 v[192:193], v[176:177], v[36:37], v[192:193]
	v_pk_fma_f32 v[194:195], v[174:175], v[36:37], v[194:195]
	v_pk_fma_f32 v[196:197], v[172:173], v[36:37], v[196:197]
	v_pk_fma_f32 v[198:199], v[170:171], v[36:37], v[198:199]
	v_pk_fma_f32 v[200:201], v[168:169], v[36:37], v[200:201]
	v_pk_fma_f32 v[202:203], v[166:167], v[36:37], v[202:203]
	v_pk_fma_f32 v[204:205], v[164:165], v[36:37], v[204:205]
	v_pk_fma_f32 v[206:207], v[162:163], v[36:37], v[206:207]
	v_pk_fma_f32 v[208:209], v[160:161], v[36:37], v[208:209]
	v_pk_fma_f32 v[210:211], v[158:159], v[36:37], v[210:211]
	v_pk_fma_f32 v[212:213], v[156:157], v[36:37], v[212:213]
	v_pk_fma_f32 v[214:215], v[154:155], v[36:37], v[214:215]
	v_pk_fma_f32 v[216:217], v[152:153], v[36:37], v[216:217]
	v_pk_fma_f32 v[218:219], v[150:151], v[36:37], v[218:219]
	v_pk_fma_f32 v[220:221], v[148:149], v[36:37], v[220:221]
	v_pk_fma_f32 v[190:191], v[180:181], v[38:39], v[190:191]
	v_pk_fma_f32 v[192:193], v[178:179], v[38:39], v[192:193]
	v_pk_fma_f32 v[194:195], v[176:177], v[38:39], v[194:195]
	v_pk_fma_f32 v[196:197], v[174:175], v[38:39], v[196:197]
	v_pk_fma_f32 v[198:199], v[172:173], v[38:39], v[198:199]
	v_pk_fma_f32 v[200:201], v[170:171], v[38:39], v[200:201]
	v_pk_fma_f32 v[202:203], v[168:169], v[38:39], v[202:203]
	v_pk_fma_f32 v[204:205], v[166:167], v[38:39], v[204:205]
	v_pk_fma_f32 v[206:207], v[164:165], v[38:39], v[206:207]
	v_pk_fma_f32 v[208:209], v[162:163], v[38:39], v[208:209]
	v_pk_fma_f32 v[210:211], v[160:161], v[38:39], v[210:211]
	v_pk_fma_f32 v[212:213], v[158:159], v[38:39], v[212:213]
	v_pk_fma_f32 v[214:215], v[156:157], v[38:39], v[214:215]
	v_pk_fma_f32 v[216:217], v[154:155], v[38:39], v[216:217]
	v_pk_fma_f32 v[218:219], v[152:153], v[38:39], v[218:219]
	v_pk_fma_f32 v[220:221], v[150:151], v[38:39], v[220:221]
	v_pk_fma_f32 v[190:191], v[182:183], v[50:51], v[190:191]
	v_pk_fma_f32 v[192:193], v[180:181], v[50:51], v[192:193]
	v_pk_fma_f32 v[194:195], v[178:179], v[50:51], v[194:195]
	v_pk_fma_f32 v[196:197], v[176:177], v[50:51], v[196:197]
	v_pk_fma_f32 v[198:199], v[174:175], v[50:51], v[198:199]
	v_pk_fma_f32 v[200:201], v[172:173], v[50:51], v[200:201]
	v_pk_fma_f32 v[202:203], v[170:171], v[50:51], v[202:203]
	v_pk_fma_f32 v[204:205], v[168:169], v[50:51], v[204:205]
	v_pk_fma_f32 v[206:207], v[166:167], v[50:51], v[206:207]
	v_pk_fma_f32 v[208:209], v[164:165], v[50:51], v[208:209]
	v_pk_fma_f32 v[210:211], v[162:163], v[50:51], v[210:211]
	v_pk_fma_f32 v[212:213], v[160:161], v[50:51], v[212:213]
	v_pk_fma_f32 v[214:215], v[158:159], v[50:51], v[214:215]
	v_pk_fma_f32 v[216:217], v[156:157], v[50:51], v[216:217]
	v_pk_fma_f32 v[218:219], v[154:155], v[50:51], v[218:219]
; DI void conv_item(LAS unsigned char* lds, int item, const bf16_t* P, const float* cw, const float* cb, const float* lng, const float* lnb, bf16_t* MIX) {
;     ...
;         for (int i = 0; i < 32; ++i)
; #pragma unroll
;             for (int k = 0; k < 31; ++k) y[i] += w[k] * uw[i + k];
	v_pk_fma_f32 v[220:221], v[152:153], v[50:51], v[220:221]
	v_pk_fma_f32 v[190:191], v[184:185], v[52:53], v[190:191]
	v_pk_fma_f32 v[192:193], v[182:183], v[52:53], v[192:193]
	v_pk_fma_f32 v[194:195], v[180:181], v[52:53], v[194:195]
	v_pk_fma_f32 v[196:197], v[178:179], v[52:53], v[196:197]
	v_pk_fma_f32 v[198:199], v[176:177], v[52:53], v[198:199]
	v_pk_fma_f32 v[200:201], v[174:175], v[52:53], v[200:201]
	v_pk_fma_f32 v[202:203], v[172:173], v[52:53], v[202:203]
	v_pk_fma_f32 v[204:205], v[170:171], v[52:53], v[204:205]
	v_pk_fma_f32 v[206:207], v[168:169], v[52:53], v[206:207]
	v_pk_fma_f32 v[208:209], v[166:167], v[52:53], v[208:209]
	v_pk_fma_f32 v[210:211], v[164:165], v[52:53], v[210:211]
	v_pk_fma_f32 v[212:213], v[162:163], v[52:53], v[212:213]
	v_pk_fma_f32 v[214:215], v[160:161], v[52:53], v[214:215]
	v_pk_fma_f32 v[216:217], v[158:159], v[52:53], v[216:217]
	v_pk_fma_f32 v[218:219], v[156:157], v[52:53], v[218:219]
	v_pk_fma_f32 v[220:221], v[154:155], v[52:53], v[220:221]
	v_pk_fma_f32 v[190:191], v[186:187], v[54:55], v[190:191]
	v_pk_fma_f32 v[192:193], v[184:185], v[54:55], v[192:193]
	v_pk_fma_f32 v[194:195], v[182:183], v[54:55], v[194:195]
	v_pk_fma_f32 v[196:197], v[180:181], v[54:55], v[196:197]
	v_pk_fma_f32 v[198:199], v[178:179], v[54:55], v[198:199]
	v_pk_fma_f32 v[200:201], v[176:177], v[54:55], v[200:201]
	v_pk_fma_f32 v[202:203], v[174:175], v[54:55], v[202:203]
	v_pk_fma_f32 v[204:205], v[172:173], v[54:55], v[204:205]
	v_pk_fma_f32 v[206:207], v[170:171], v[54:55], v[206:207]
	v_pk_fma_f32 v[208:209], v[168:169], v[54:55], v[208:209]
	v_pk_fma_f32 v[210:211], v[166:167], v[54:55], v[210:211]
	v_pk_fma_f32 v[212:213], v[164:165], v[54:55], v[212:213]
	v_pk_fma_f32 v[214:215], v[162:163], v[54:55], v[214:215]
	v_pk_fma_f32 v[216:217], v[160:161], v[54:55], v[216:217]
	v_pk_fma_f32 v[218:219], v[158:159], v[54:55], v[218:219]
	v_pk_fma_f32 v[220:221], v[156:157], v[54:55], v[220:221]
	v_pk_fma_f32 v[192:193], v[186:187], v[56:57], v[192:193]
	v_pk_fma_f32 v[194:195], v[184:185], v[56:57], v[194:195]
	v_pk_fma_f32 v[196:197], v[182:183], v[56:57], v[196:197]
	v_pk_fma_f32 v[198:199], v[180:181], v[56:57], v[198:199]
	v_pk_fma_f32 v[200:201], v[178:179], v[56:57], v[200:201]
	v_pk_fma_f32 v[202:203], v[176:177], v[56:57], v[202:203]
	v_pk_fma_f32 v[204:205], v[174:175], v[56:57], v[204:205]
	v_pk_fma_f32 v[206:207], v[172:173], v[56:57], v[206:207]
	v_pk_fma_f32 v[208:209], v[170:171], v[56:57], v[208:209]
	v_pk_fma_f32 v[210:211], v[168:169], v[56:57], v[210:211]
	v_pk_fma_f32 v[212:213], v[166:167], v[56:57], v[212:213]
	v_pk_fma_f32 v[214:215], v[164:165], v[56:57], v[214:215]
	v_pk_fma_f32 v[216:217], v[162:163], v[56:57], v[216:217]
	v_pk_fma_f32 v[218:219], v[160:161], v[56:57], v[218:219]
	v_pk_fma_f32 v[220:221], v[158:159], v[56:57], v[220:221]
	v_pk_fma_f32 v[194:195], v[186:187], v[58:59], v[194:195]
	v_pk_fma_f32 v[196:197], v[184:185], v[58:59], v[196:197]
	v_pk_fma_f32 v[198:199], v[182:183], v[58:59], v[198:199]
	v_pk_fma_f32 v[200:201], v[180:181], v[58:59], v[200:201]
	v_pk_fma_f32 v[202:203], v[178:179], v[58:59], v[202:203]
	v_pk_fma_f32 v[204:205], v[176:177], v[58:59], v[204:205]
	v_pk_fma_f32 v[206:207], v[174:175], v[58:59], v[206:207]
	v_pk_fma_f32 v[208:209], v[172:173], v[58:59], v[208:209]
	v_pk_fma_f32 v[210:211], v[170:171], v[58:59], v[210:211]
	v_pk_fma_f32 v[212:213], v[168:169], v[58:59], v[212:213]
	v_pk_fma_f32 v[214:215], v[166:167], v[58:59], v[214:215]
	v_pk_fma_f32 v[216:217], v[164:165], v[58:59], v[216:217]
	v_pk_fma_f32 v[218:219], v[162:163], v[58:59], v[218:219]
	v_pk_fma_f32 v[220:221], v[160:161], v[58:59], v[220:221]
	v_pk_fma_f32 v[196:197], v[186:187], v[60:61], v[196:197]
	v_pk_fma_f32 v[198:199], v[184:185], v[60:61], v[198:199]
	v_pk_fma_f32 v[200:201], v[182:183], v[60:61], v[200:201]
	v_pk_fma_f32 v[202:203], v[180:181], v[60:61], v[202:203]
	v_add_u32_e32 v26, s36, v80
	v_pk_fma_f32 v[204:205], v[178:179], v[60:61], v[204:205]
	v_pk_fma_f32 v[206:207], v[176:177], v[60:61], v[206:207]
	v_pk_fma_f32 v[208:209], v[174:175], v[60:61], v[208:209]
	v_pk_fma_f32 v[210:211], v[172:173], v[60:61], v[210:211]
	v_pk_fma_f32 v[212:213], v[170:171], v[60:61], v[212:213]
	v_pk_fma_f32 v[214:215], v[168:169], v[60:61], v[214:215]
	v_pk_fma_f32 v[216:217], v[166:167], v[60:61], v[216:217]
	v_pk_fma_f32 v[218:219], v[164:165], v[60:61], v[218:219]
	v_mov_b64_e32 v[24:25], s[62:63]
	v_pk_fma_f32 v[220:221], v[162:163], v[60:61], v[220:221]
	v_pk_fma_f32 v[198:199], v[186:187], v[62:63], v[198:199]
	v_pk_fma_f32 v[200:201], v[184:185], v[62:63], v[200:201]
	v_pk_fma_f32 v[202:203], v[182:183], v[62:63], v[202:203]
	v_pk_fma_f32 v[204:205], v[180:181], v[62:63], v[204:205]
	v_pk_fma_f32 v[206:207], v[178:179], v[62:63], v[206:207]
	v_pk_fma_f32 v[208:209], v[176:177], v[62:63], v[208:209]
	v_pk_fma_f32 v[210:211], v[174:175], v[62:63], v[210:211]
	v_lshl_add_u64 v[0:1], v[42:43], 0, s[12:13]
	v_pk_fma_f32 v[212:213], v[172:173], v[62:63], v[212:213]
	v_pk_fma_f32 v[214:215], v[170:171], v[62:63], v[214:215]
	v_pk_fma_f32 v[216:217], v[168:169], v[62:63], v[216:217]
	v_pk_fma_f32 v[218:219], v[166:167], v[62:63], v[218:219]
	v_pk_fma_f32 v[220:221], v[164:165], v[62:63], v[220:221]
	v_pk_fma_f32 v[200:201], v[186:187], v[64:65], v[200:201]
	v_pk_fma_f32 v[202:203], v[184:185], v[64:65], v[202:203]
	v_pk_fma_f32 v[204:205], v[182:183], v[64:65], v[204:205]
	v_lshl_add_u64 v[4:5], v[44:45], 0, s[12:13]
	v_pk_fma_f32 v[206:207], v[180:181], v[64:65], v[206:207]
	v_pk_fma_f32 v[208:209], v[178:179], v[64:65], v[208:209]
	v_pk_fma_f32 v[210:211], v[176:177], v[64:65], v[210:211]
; DI void conv_item(LAS unsigned char* lds, int item, const bf16_t* P, const float* cw, const float* cb, const float* lng, const float* lnb, bf16_t* MIX) {
;     ...
;         for (int i = 0; i < 32; ++i)
; #pragma unroll
;             for (int k = 0; k < 31; ++k) y[i] += w[k] * uw[i + k];
;     }
;     __syncthreads();
; #pragma unroll
;     for (int i = 0; i < 32; ++i) U[(tq * 32 + i) * 128 + c] = y[i];
;     __syncthreads();
	v_pk_fma_f32 v[212:213], v[174:175], v[64:65], v[212:213]
	v_pk_fma_f32 v[214:215], v[172:173], v[64:65], v[214:215]
	v_pk_fma_f32 v[216:217], v[170:171], v[64:65], v[216:217]
	v_pk_fma_f32 v[218:219], v[168:169], v[64:65], v[218:219]
	v_pk_fma_f32 v[220:221], v[166:167], v[64:65], v[220:221]
	s_lshl_b32 s12, s37, 1
	v_pk_fma_f32 v[202:203], v[186:187], v[66:67], v[202:203]
	v_pk_fma_f32 v[204:205], v[184:185], v[66:67], v[204:205]
	v_pk_fma_f32 v[206:207], v[182:183], v[66:67], v[206:207]
	v_pk_fma_f32 v[208:209], v[180:181], v[66:67], v[208:209]
	v_pk_fma_f32 v[210:211], v[178:179], v[66:67], v[210:211]
	v_pk_fma_f32 v[212:213], v[176:177], v[66:67], v[212:213]
	v_pk_fma_f32 v[214:215], v[174:175], v[66:67], v[214:215]
	v_pk_fma_f32 v[216:217], v[172:173], v[66:67], v[216:217]
	v_mad_i64_i32 v[2:3], s[26:27], v26, s30, v[24:25]
	v_pk_fma_f32 v[218:219], v[170:171], v[66:67], v[218:219]
	v_pk_fma_f32 v[220:221], v[168:169], v[66:67], v[220:221]
	v_pk_fma_f32 v[204:205], v[186:187], v[92:93], v[204:205]
	v_pk_fma_f32 v[206:207], v[184:185], v[92:93], v[206:207]
	v_pk_fma_f32 v[208:209], v[182:183], v[92:93], v[208:209]
	v_pk_fma_f32 v[210:211], v[180:181], v[92:93], v[210:211]
	v_pk_fma_f32 v[212:213], v[178:179], v[92:93], v[212:213]
	v_pk_fma_f32 v[214:215], v[176:177], v[92:93], v[214:215]
	v_lshl_add_u64 v[2:3], v[2:3], 0, s[12:13]
	v_pk_fma_f32 v[216:217], v[174:175], v[92:93], v[216:217]
	v_pk_fma_f32 v[218:219], v[172:173], v[92:93], v[218:219]
	v_pk_fma_f32 v[220:221], v[170:171], v[92:93], v[220:221]
	v_pk_fma_f32 v[206:207], v[186:187], v[94:95], v[206:207]
	v_pk_fma_f32 v[208:209], v[184:185], v[94:95], v[208:209]
	v_pk_fma_f32 v[210:211], v[182:183], v[94:95], v[210:211]
	v_pk_fma_f32 v[212:213], v[180:181], v[94:95], v[212:213]
	v_pk_fma_f32 v[214:215], v[178:179], v[94:95], v[214:215]
	v_mov_b32_e32 v47, v41
	v_pk_fma_f32 v[216:217], v[176:177], v[94:95], v[216:217]
	v_pk_fma_f32 v[218:219], v[174:175], v[94:95], v[218:219]
	v_pk_fma_f32 v[220:221], v[172:173], v[94:95], v[220:221]
	v_pk_fma_f32 v[208:209], v[186:187], v[96:97], v[208:209]
	v_pk_fma_f32 v[210:211], v[184:185], v[96:97], v[210:211]
	v_pk_fma_f32 v[212:213], v[182:183], v[96:97], v[212:213]
	v_pk_fma_f32 v[214:215], v[180:181], v[96:97], v[214:215]
	v_pk_fma_f32 v[216:217], v[178:179], v[96:97], v[216:217]
	v_lshl_add_u64 v[2:3], v[2:3], 0, v[46:47]
	v_pk_fma_f32 v[218:219], v[176:177], v[96:97], v[218:219]
	v_pk_fma_f32 v[220:221], v[174:175], v[96:97], v[220:221]
	v_pk_fma_f32 v[210:211], v[186:187], v[98:99], v[210:211]
	v_pk_fma_f32 v[212:213], v[184:185], v[98:99], v[212:213]
	v_pk_fma_f32 v[214:215], v[182:183], v[98:99], v[214:215]
	v_pk_fma_f32 v[216:217], v[180:181], v[98:99], v[216:217]
	v_pk_fma_f32 v[218:219], v[178:179], v[98:99], v[218:219]
	v_pk_fma_f32 v[220:221], v[176:177], v[98:99], v[220:221]
	v_add_co_u32_e32 v6, vcc, s31, v2
	v_pk_fma_f32 v[212:213], v[186:187], v[100:101], v[212:213]
	v_pk_fma_f32 v[214:215], v[184:185], v[100:101], v[214:215]
	v_pk_fma_f32 v[216:217], v[182:183], v[100:101], v[216:217]
	v_pk_fma_f32 v[218:219], v[180:181], v[100:101], v[218:219]
	v_pk_fma_f32 v[220:221], v[178:179], v[100:101], v[220:221]
	v_pk_fma_f32 v[214:215], v[186:187], v[102:103], v[214:215]
	v_pk_fma_f32 v[216:217], v[184:185], v[102:103], v[216:217]
	v_pk_fma_f32 v[218:219], v[182:183], v[102:103], v[218:219]
	v_addc_co_u32_e32 v7, vcc, 0, v3, vcc
	v_pk_fma_f32 v[220:221], v[180:181], v[102:103], v[220:221]
	v_pk_fma_f32 v[216:217], v[186:187], v[104:105], v[216:217]
	v_pk_fma_f32 v[218:219], v[184:185], v[104:105], v[218:219]
	v_pk_fma_f32 v[220:221], v[182:183], v[104:105], v[220:221]
	v_pk_fma_f32 v[218:219], v[186:187], v[106:107], v[218:219]
	v_pk_fma_f32 v[220:221], v[184:185], v[106:107], v[220:221]
	v_pk_fma_f32 v[220:221], v[186:187], v[108:109], v[220:221]
	ds_write_b64 v251, v[190:191]
	ds_write_b64 v251, v[192:193] offset:512
	ds_write_b64 v251, v[194:195] offset:1024
	ds_write_b64 v251, v[196:197] offset:1536
	ds_write_b64 v251, v[198:199] offset:2048
	ds_write_b64 v251, v[200:201] offset:2560
	ds_write_b64 v251, v[202:203] offset:3072
	ds_write_b64 v251, v[204:205] offset:3584
	ds_write_b64 v251, v[206:207] offset:4096
	ds_write_b64 v251, v[208:209] offset:4608
	ds_write_b64 v251, v[210:211] offset:5120
	ds_write_b64 v251, v[212:213] offset:5632
	ds_write_b64 v251, v[214:215] offset:6144
	ds_write_b64 v251, v[216:217] offset:6656
	ds_write_b64 v251, v[218:219] offset:7168
	ds_write_b64 v251, v[220:221] offset:7680
	s_waitcnt lgkmcnt(0)
	s_barrier
; #define LAS __attribute__((address_space(3)))
; DI float dot4(const f32x4 a) { return (a[0] * a[0] + a[1] * a[1]) + (a[2] * a[2] + a[3] * a[3]); }
; DI void conv_item(LAS unsigned char* lds, int item, const bf16_t* P, const float* cw, const float* cb, const float* lng, const float* lnb, bf16_t* MIX) {
;     ...
;         for (int it = 0; it < 4; ++it) {
;             const int t = wid * 16 + it * 4 + ts;
;             const size_t row = (size_t)(tt0 + t);
;             const u32x2 za = *(const u32x2*)(P + row * LDP + 2048 + cbase + ca), zb = *(const u32x2*)(P + row * LDP + 2048 + cbase + cb2);
;             f32x4 va = *(LAS f32x4*)(U + t * 128 + ca), vb = *(LAS f32x4*)(U + t * 128 + cb2);
;             float sm = ((va[0] + va[1]) + (va[2] + va[3])) + ((vb[0] + vb[1]) + (vb[2] + vb[3]));
;             sm += __shfl_xor(sm, 1); sm += __shfl_xor(sm, 2); sm += __shfl_xor(sm, 4); sm += __shfl_xor(sm, 8);
;             const float mu = sm * (1.f / 128.f);
;             va = va - mu; vb = vb - mu;
;             float sq = dot4(va) + dot4(vb);
;             sq += __shfl_xor(sq, 1); sq += __shfl_xor(sq, 2); sq += __shfl_xor(sq, 4); sq += __shfl_xor(sq, 8);
;             const float rstd = rsqrtf(sq * (1.f / 128.f) + EPS_);
	global_load_dwordx2 v[28:29], v[6:7], off
	v_lshl_add_u64 v[2:3], v[2:3], 0, s[18:19]
	ds_read_b128 v[20:23], v85
	ds_read_b128 v[16:19], v85 offset:256
	global_load_dwordx2 v[36:37], v[2:3], off offset:128
	s_add_u32 s26, s80, s12
	v_ashrrev_i32_e32 v27, 31, v26
	s_waitcnt lgkmcnt(1)
	v_mov_b32_e32 v6, v20
	s_waitcnt lgkmcnt(0)
	v_mov_b32_e32 v7, v16
	v_mov_b32_e32 v8, v21
	v_mov_b32_e32 v9, v17
	v_pk_add_f32 v[6:7], v[6:7], v[8:9]
	v_mov_b32_e32 v8, v22
	v_mov_b32_e32 v9, v18
	v_mov_b32_e32 v10, v23
	v_mov_b32_e32 v11, v19
	v_pk_add_f32 v[8:9], v[8:9], v[10:11]
	s_addc_u32 s27, s81, 0
	v_pk_add_f32 v[6:7], v[6:7], v[8:9]
	s_add_i32 s35, s35, s58
	v_add_f32_e32 v6, v6, v7
	s_nop 1
	v_mov_b32_dpp v7, v6 quad_perm:[1,0,3,2] row_mask:0xf bank_mask:0xf
	s_add_i32 s28, s28, s29
	s_waitcnt lgkmcnt(0)
	v_add_f32_e32 v2, v6, v7
	s_nop 1
	v_mov_b32_dpp v3, v2 quad_perm:[2,3,0,1] row_mask:0xf bank_mask:0xf
	s_waitcnt lgkmcnt(0)
	v_add_f32_e32 v6, v2, v3
	s_nop 1
	v_mov_b32_dpp v7, v6 row_half_mirror row_mask:0xf bank_mask:0xf
	global_load_dwordx4 v[8:11], v[0:1], off
	s_nop 0
	global_load_dwordx4 v[0:3], v[0:1], off offset:256
	s_waitcnt lgkmcnt(0)
	v_add_f32_e32 v30, v6, v7
	s_nop 1
	v_mov_b32_dpp v31, v30 row_mirror row_mask:0xf bank_mask:0xf
	global_load_dwordx4 v[12:15], v[4:5], off
	s_nop 0
	global_load_dwordx4 v[4:7], v[4:5], off offset:256
	s_waitcnt lgkmcnt(0)
	v_add_f32_e32 v30, v30, v31
	v_fmamk_f32 v21, v30, 0xbc000000, v21
	v_fmamk_f32 v17, v30, 0xbc000000, v17
	v_fmamk_f32 v39, v30, 0xbc000000, v23
	v_fmamk_f32 v38, v30, 0xbc000000, v22
	v_fmac_f32_e32 v20, 0xbc000000, v30
	v_fmamk_f32 v23, v30, 0xbc000000, v19
	v_fmamk_f32 v22, v30, 0xbc000000, v18
	v_fmac_f32_e32 v16, 0xbc000000, v30
	v_mov_b32_e32 v30, v21
	v_mov_b32_e32 v31, v17
	v_mov_b32_e32 v18, v20
	v_mov_b32_e32 v19, v16
	v_pk_mul_f32 v[30:31], v[30:31], v[30:31]
	v_mov_b32_e32 v32, v39
	v_mov_b32_e32 v33, v23
	v_pk_fma_f32 v[18:19], v[18:19], v[18:19], v[30:31]
	v_mov_b32_e32 v30, v38
	v_mov_b32_e32 v31, v22
	v_pk_mul_f32 v[32:33], v[32:33], v[32:33]
	s_waitcnt vmcnt(5)
	v_lshlrev_b32_e32 v50, 16, v28
	v_and_b32_e32 v51, 0xffff0000, v28
	v_mul_f32_e32 v28, 0xbfb8aa3b, v50
	v_pk_fma_f32 v[30:31], v[30:31], v[30:31], v[32:33]
	v_exp_f32_e32 v28, v28
	v_mul_f32_e32 v32, 0xbfb8aa3b, v51
	v_exp_f32_e32 v32, v32
	v_pk_add_f32 v[18:19], v[18:19], v[30:31]
	v_add_f32_e32 v28, 1.0, v28
	v_rcp_f32_e32 v52, v28
	v_add_f32_e32 v28, 1.0, v32
	v_rcp_f32_e32 v53, v28
	v_lshlrev_b32_e32 v54, 16, v29
	v_and_b32_e32 v55, 0xffff0000, v29
	ds_read_b128 v[28:31], v87
	ds_read_b128 v[32:35], v87 offset:256
	v_mul_f32_e32 v40, 0xbfb8aa3b, v54
	v_exp_f32_e32 v40, v40
	v_mul_f32_e32 v49, 0xbfb8aa3b, v55
	s_waitcnt lgkmcnt(1)
	v_mov_b32_e32 v56, v28
	s_waitcnt lgkmcnt(0)
	v_mov_b32_e32 v57, v32
	v_mov_b32_e32 v58, v29
	v_mov_b32_e32 v59, v33
	v_pk_add_f32 v[56:57], v[56:57], v[58:59]
	v_mov_b32_e32 v58, v30
	v_mov_b32_e32 v59, v34
	v_mov_b32_e32 v60, v31
	v_mov_b32_e32 v61, v35
	v_pk_add_f32 v[58:59], v[58:59], v[60:61]
	v_exp_f32_e32 v49, v49
	v_pk_add_f32 v[56:57], v[56:57], v[58:59]
	v_add_f32_e32 v40, 1.0, v40
	v_add_f32_e32 v58, v56, v57
	s_nop 1
	v_mov_b32_dpp v59, v58 quad_perm:[1,0,3,2] row_mask:0xf bank_mask:0xf
	v_rcp_f32_e32 v56, v40
	v_add_f32_e32 v40, 1.0, v49
	v_rcp_f32_e32 v57, v40
	v_pk_mul_f32 v[50:51], v[52:53], v[50:51]
	s_waitcnt lgkmcnt(0)
	v_add_f32_e32 v40, v58, v59
	s_nop 1
	v_mov_b32_dpp v49, v40 quad_perm:[2,3,0,1] row_mask:0xf bank_mask:0xf
	s_waitcnt vmcnt(4)
	v_lshlrev_b32_e32 v58, 16, v36
	v_mul_f32_e32 v59, 0xbfb8aa3b, v58
	v_exp_f32_e32 v60, v59
	v_and_b32_e32 v59, 0xffff0000, v36
	s_waitcnt lgkmcnt(0)
	v_add_f32_e32 v36, v40, v49
	s_nop 1
	v_mov_b32_dpp v40, v36 row_half_mirror row_mask:0xf bank_mask:0xf
	v_add_f32_e32 v49, 1.0, v60
	v_mul_f32_e32 v60, 0xbfb8aa3b, v59
	v_exp_f32_e32 v61, v60
	v_rcp_f32_e32 v60, v49
	s_waitcnt lgkmcnt(0)
	v_add_f32_e32 v40, v36, v40
	s_nop 1
	v_mov_b32_dpp v49, v40 row_mirror row_mask:0xf bank_mask:0xf
	v_add_f32_e32 v36, 1.0, v61
	v_rcp_f32_e32 v61, v36
	v_pk_mul_f32 v[52:53], v[56:57], v[54:55]
	v_lshlrev_b32_e32 v36, 16, v37
	s_waitcnt lgkmcnt(0)
	v_add_f32_e32 v40, v40, v49
	v_fmamk_f32 v29, v40, 0xbc000000, v29
	v_fmamk_f32 v33, v40, 0xbc000000, v33
	v_fmamk_f32 v31, v40, 0xbc000000, v31
	v_fmac_f32_e32 v28, 0xbc000000, v40
	v_fmamk_f32 v35, v40, 0xbc000000, v35
	v_fmac_f32_e32 v32, 0xbc000000, v40
	v_mov_b32_e32 v64, v29
	v_mov_b32_e32 v65, v33
	v_fmamk_f32 v30, v40, 0xbc000000, v30
	v_fmamk_f32 v34, v40, 0xbc000000, v34
	v_mov_b32_e32 v62, v28
	v_mov_b32_e32 v63, v32
	v_pk_mul_f32 v[64:65], v[64:65], v[64:65]
	v_mov_b32_e32 v66, v31
	v_mov_b32_e32 v67, v35
	v_pk_fma_f32 v[62:63], v[62:63], v[62:63], v[64:65]
	v_mov_b32_e32 v64, v30
	v_mov_b32_e32 v65, v34
	v_pk_mul_f32 v[66:67], v[66:67], v[66:67]
	v_pk_mul_f32 v[54:55], v[60:61], v[58:59]
	v_pk_fma_f32 v[64:65], v[64:65], v[64:65], v[66:67]
	v_and_b32_e32 v37, 0xffff0000, v37
	v_pk_add_f32 v[62:63], v[62:63], v[64:65]
	v_mov_b32_e32 v65, v18
	v_mov_b32_e32 v64, v62
	v_mov_b32_e32 v18, v63
	v_pk_add_f32 v[18:19], v[64:65], v[18:19]
	s_nop 1
	v_mov_b32_dpp v63, v19 quad_perm:[1,0,3,2] row_mask:0xf bank_mask:0xf
	s_nop 1
	v_mov_b32_dpp v62, v18 quad_perm:[1,0,3,2] row_mask:0xf bank_mask:0xf
	v_mul_f32_e32 v40, 0xbfb8aa3b, v36
	v_exp_f32_e32 v40, v40
	v_mul_f32_e32 v49, 0xbfb8aa3b, v37
	v_exp_f32_e32 v49, v49
	s_waitcnt lgkmcnt(0)
	v_pk_add_f32 v[18:19], v[18:19], v[62:63]
	s_nop 1
	v_mov_b32_dpp v63, v19 quad_perm:[2,3,0,1] row_mask:0xf bank_mask:0xf
	s_nop 1
	v_mov_b32_dpp v62, v18 quad_perm:[2,3,0,1] row_mask:0xf bank_mask:0xf
	v_add_f32_e32 v40, 1.0, v40
	v_rcp_f32_e32 v64, v40
	v_add_f32_e32 v40, 1.0, v49
	v_rcp_f32_e32 v65, v40
	s_waitcnt lgkmcnt(0)
; DI float siluf_(float x) { return x * frcp(1.f + fexp(-x)); }
; DI float dot4(const f32x4 a) { return (a[0] * a[0] + a[1] * a[1]) + (a[2] * a[2] + a[3] * a[3]); }
; DI void conv_item(LAS unsigned char* lds, int item, const bf16_t* P, const float* cw, const float* cb, const float* lng, const float* lnb, bf16_t* MIX) {
;     ...
;             float sq = dot4(va) + dot4(vb);
;             sq += __shfl_xor(sq, 1); sq += __shfl_xor(sq, 2); sq += __shfl_xor(sq, 4); sq += __shfl_xor(sq, 8);
;             const float rstd = rsqrtf(sq * (1.f / 128.f) + EPS_);
;             f32x4 oa = va * rstd * ga + ba, ob = vb * rstd * gb + bb;
;             oa[0] = siluf_(oa[0]) * siluf_(bflo(za.x)); oa[1] = siluf_(oa[1]) * siluf_(bfhi(za.x)); oa[2] = siluf_(oa[2]) * siluf_(bflo(za.y)); oa[3] = siluf_(oa[3]) * siluf_(bfhi(za.y));
	v_pk_add_f32 v[18:19], v[18:19], v[62:63]
	s_nop 1
	v_mov_b32_dpp v63, v19 row_half_mirror row_mask:0xf bank_mask:0xf
	s_nop 1
	v_mov_b32_dpp v62, v18 row_half_mirror row_mask:0xf bank_mask:0xf
	v_pk_mul_f32 v[36:37], v[64:65], v[36:37]
	s_waitcnt lgkmcnt(0)
	v_pk_add_f32 v[56:57], v[18:19], v[62:63]
	s_nop 1
	v_mov_b32_dpp v59, v57 row_mirror row_mask:0xf bank_mask:0xf
	s_nop 1
	v_mov_b32_dpp v58, v56 row_mirror row_mask:0xf bank_mask:0xf
	v_lshlrev_b64 v[18:19], 12, v[26:27]
	v_mov_b64_e32 v[26:27], s[22:23]
	v_lshl_add_u64 v[18:19], s[26:27], 0, v[18:19]
	v_lshl_add_u64 v[60:61], v[18:19], 0, v[46:47]
	s_waitcnt lgkmcnt(0)
	v_pk_add_f32 v[56:57], v[56:57], v[58:59]
	v_add_u32_e32 v18, s36, v86
	v_pk_fma_f32 v[56:57], v[56:57], s[20:21], v[26:27] op_sel_hi:[1,0,0]
	v_mad_i64_i32 v[58:59], s[38:39], v18, s30, v[24:25]
	v_mul_f32_e32 v19, 0x4b800000, v57
	v_cmp_gt_f32_e32 vcc, s34, v57
	v_lshl_add_u64 v[58:59], v[58:59], 0, s[12:13]
	v_lshl_add_u64 v[58:59], v[58:59], 0, v[46:47]
	v_cndmask_b32_e32 v19, v57, v19, vcc
	v_rsq_f32_e32 v19, v19
	s_nop 0
	v_mul_f32_e32 v40, 0x45800000, v19
	v_cndmask_b32_e32 v40, v19, v40, vcc
	v_pk_mul_f32 v[20:21], v[20:21], v[40:41] op_sel_hi:[1,0]
	v_pk_mul_f32 v[38:39], v[38:39], v[40:41] op_sel_hi:[1,0]
	s_waitcnt vmcnt(1)
	v_pk_fma_f32 v[20:21], v[8:9], v[20:21], v[12:13]
	v_pk_fma_f32 v[38:39], v[10:11], v[38:39], v[14:15]
	v_mul_f32_e32 v19, 0xbfb8aa3b, v20
	v_exp_f32_e32 v19, v19
	v_mul_f32_e32 v49, 0xbfb8aa3b, v21
	v_exp_f32_e32 v49, v49
	v_pk_mul_f32 v[16:17], v[16:17], v[40:41] op_sel_hi:[1,0]
	v_add_f32_e32 v19, 1.0, v19
	v_rcp_f32_e32 v62, v19
	v_add_f32_e32 v19, 1.0, v49
	v_rcp_f32_e32 v63, v19
	v_mul_f32_e32 v19, 0xbfb8aa3b, v38
	v_pk_mul_f32 v[22:23], v[22:23], v[40:41] op_sel_hi:[1,0]
	v_exp_f32_e32 v19, v19
	v_mul_f32_e32 v40, 0xbfb8aa3b, v39
	v_exp_f32_e32 v40, v40
	v_pk_mul_f32 v[20:21], v[20:21], v[62:63]
	v_add_f32_e32 v19, 1.0, v19
	s_waitcnt vmcnt(0)
	v_pk_fma_f32 v[16:17], v[0:1], v[16:17], v[4:5]
	v_pk_mul_f32 v[20:21], v[50:51], v[20:21]
	v_rcp_f32_e32 v50, v19
	v_add_f32_e32 v19, 1.0, v40
	v_rcp_f32_e32 v51, v19
	v_mul_f32_e32 v19, 0xbfb8aa3b, v16
	v_exp_f32_e32 v19, v19
	v_mul_f32_e32 v40, 0xbfb8aa3b, v17
	v_exp_f32_e32 v40, v40
	v_pk_fma_f32 v[22:23], v[2:3], v[22:23], v[6:7]
	v_add_f32_e32 v19, 1.0, v19
	v_pk_mul_f32 v[38:39], v[38:39], v[50:51]
	v_rcp_f32_e32 v50, v19
	v_add_f32_e32 v19, 1.0, v40
	v_mul_f32_e32 v40, 0xbfb8aa3b, v22
	v_exp_f32_e32 v40, v40
	v_mul_f32_e32 v49, 0xbfb8aa3b, v23
	v_exp_f32_e32 v49, v49
	v_rcp_f32_e32 v51, v19
	v_add_f32_e32 v19, 1.0, v40
	v_rcp_f32_e32 v62, v19
	v_add_f32_e32 v19, 1.0, v49
	v_rcp_f32_e32 v63, v19
	v_pk_mul_f32 v[16:17], v[16:17], v[50:51]
	v_pk_mul_f32 v[38:39], v[52:53], v[38:39]
	v_pk_mul_f32 v[16:17], v[54:55], v[16:17]
	v_pk_mul_f32 v[22:23], v[22:23], v[62:63]
	v_cvt_pk_bf16_f32 v16, v16, v17
	v_pk_mul_f32 v[22:23], v[36:37], v[22:23]
	v_cvt_pk_bf16_f32 v20, v20, v21
	v_cvt_pk_bf16_f32 v17, v22, v23
	v_cvt_pk_bf16_f32 v21, v38, v39
	global_store_dwordx2 v[60:61], v[16:17], off offset:128
	v_add_co_u32_e32 v16, vcc, s31, v58
	global_store_dwordx2 v[60:61], v[20:21], off
	s_nop 0
	v_addc_co_u32_e32 v17, vcc, 0, v59, vcc
	global_load_dwordx2 v[16:17], v[16:17], off
	v_lshl_add_u64 v[20:21], v[58:59], 0, s[18:19]
	global_load_dwordx2 v[20:21], v[20:21], off offset:128
	v_mul_f32_e32 v19, 0x4b800000, v56
	v_cmp_gt_f32_e32 vcc, s34, v56
	s_waitcnt vmcnt(1)
	v_lshlrev_b32_e32 v36, 16, v16
	v_cndmask_b32_e32 v19, v56, v19, vcc
	v_rsq_f32_e32 v22, v19
	v_mul_f32_e32 v37, 0xbfb8aa3b, v36
	v_exp_f32_e32 v38, v37
	v_and_b32_e32 v37, 0xffff0000, v16
	v_mul_f32_e32 v23, 0x45800000, v22
	v_cndmask_b32_e32 v22, v22, v23, vcc
	v_pk_mul_f32 v[28:29], v[28:29], v[22:23] op_sel_hi:[1,0]
	v_pk_mul_f32 v[30:31], v[30:31], v[22:23] op_sel_hi:[1,0]
	v_pk_fma_f32 v[28:29], v[8:9], v[28:29], v[12:13]
	v_pk_mul_f32 v[32:33], v[32:33], v[22:23] op_sel_hi:[1,0]
	v_pk_mul_f32 v[22:23], v[34:35], v[22:23] op_sel_hi:[1,0]
	v_mul_f32_e32 v34, 0xbfb8aa3b, v28
	v_mul_f32_e32 v35, 0xbfb8aa3b, v29
	v_exp_f32_e32 v34, v34
	v_exp_f32_e32 v35, v35
	v_pk_fma_f32 v[30:31], v[10:11], v[30:31], v[14:15]
	v_mul_f32_e32 v16, 0xbfb8aa3b, v37
	v_add_f32_e32 v34, 1.0, v34
	v_add_f32_e32 v35, 1.0, v35
	v_rcp_f32_e32 v34, v34
	v_rcp_f32_e32 v35, v35
	v_exp_f32_e32 v16, v16
	v_pk_fma_f32 v[32:33], v[0:1], v[32:33], v[4:5]
	v_add_f32_e32 v38, 1.0, v38
	v_pk_mul_f32 v[28:29], v[28:29], v[34:35]
	v_mul_f32_e32 v34, 0xbfb8aa3b, v30
	v_exp_f32_e32 v34, v34
	v_mul_f32_e32 v35, 0xbfb8aa3b, v31
	v_exp_f32_e32 v35, v35
	v_add_f32_e32 v16, 1.0, v16
	v_rcp_f32_e32 v39, v16
	v_add_f32_e32 v16, 1.0, v34
	v_lshlrev_b32_e32 v34, 16, v17
	v_add_f32_e32 v40, 1.0, v35
	v_and_b32_e32 v35, 0xffff0000, v17
	v_mul_f32_e32 v17, 0xbfb8aa3b, v34
	v_exp_f32_e32 v49, v17
	v_mul_f32_e32 v17, 0xbfb8aa3b, v35
	v_exp_f32_e32 v51, v17
	v_rcp_f32_e32 v17, v40
	v_add_f32_e32 v40, 1.0, v49
	v_rcp_f32_e32 v50, v40
	v_add_f32_e32 v40, 1.0, v51
	v_rcp_f32_e32 v16, v16
	v_rcp_f32_e32 v51, v40
	v_rcp_f32_e32 v38, v38
	v_pk_fma_f32 v[22:23], v[2:3], v[22:23], v[6:7]
	v_pk_mul_f32 v[16:17], v[30:31], v[16:17]
	v_pk_mul_f32 v[30:31], v[50:51], v[34:35]
	v_mul_f32_e32 v34, 0xbfb8aa3b, v32
	v_mul_f32_e32 v35, 0xbfb8aa3b, v33
	v_exp_f32_e32 v34, v34
	v_exp_f32_e32 v35, v35
	v_pk_mul_f32 v[16:17], v[30:31], v[16:17]
	v_pk_mul_f32 v[36:37], v[38:39], v[36:37]
	v_add_f32_e32 v30, 1.0, v34
	v_add_f32_e32 v31, 1.0, v35
	v_rcp_f32_e32 v30, v30
	v_rcp_f32_e32 v31, v31
	s_waitcnt vmcnt(0)
; #define LAS __attribute__((address_space(3)))
; DI float dot4(const f32x4 a) { return (a[0] * a[0] + a[1] * a[1]) + (a[2] * a[2] + a[3] * a[3]); }
; DI void conv_item(LAS unsigned char* lds, int item, const bf16_t* P, const float* cw, const float* cb, const float* lng, const float* lnb, bf16_t* MIX) {
;     ...
;         for (int it = 0; it < 4; ++it) {
;             const int t = wid * 16 + it * 4 + ts;
;             const size_t row = (size_t)(tt0 + t);
;             const u32x2 za = *(const u32x2*)(P + row * LDP + 2048 + cbase + ca), zb = *(const u32x2*)(P + row * LDP + 2048 + cbase + cb2);
;             f32x4 va = *(LAS f32x4*)(U + t * 128 + ca), vb = *(LAS f32x4*)(U + t * 128 + cb2);
;             float sm = ((va[0] + va[1]) + (va[2] + va[3])) + ((vb[0] + vb[1]) + (vb[2] + vb[3]));
;             sm += __shfl_xor(sm, 1); sm += __shfl_xor(sm, 2); sm += __shfl_xor(sm, 4); sm += __shfl_xor(sm, 8);
;             const float mu = sm * (1.f / 128.f);
;             va = va - mu; vb = vb - mu;
;             float sq = dot4(va) + dot4(vb);
;             sq += __shfl_xor(sq, 1); sq += __shfl_xor(sq, 2); sq += __shfl_xor(sq, 4); sq += __shfl_xor(sq, 8);
;             const float rstd = rsqrtf(sq * (1.f / 128.f) + EPS_);
	v_lshlrev_b32_e32 v34, 16, v20
	v_mul_f32_e32 v35, 0xbfb8aa3b, v34
	v_pk_mul_f32 v[28:29], v[36:37], v[28:29]
	v_exp_f32_e32 v36, v35
	v_and_b32_e32 v35, 0xffff0000, v20
	v_mul_f32_e32 v20, 0xbfb8aa3b, v35
	v_exp_f32_e32 v20, v20
	v_pk_mul_f32 v[30:31], v[32:33], v[30:31]
	v_mul_f32_e32 v32, 0xbfb8aa3b, v22
	v_exp_f32_e32 v32, v32
	v_mul_f32_e32 v33, 0xbfb8aa3b, v23
	v_exp_f32_e32 v33, v33
	v_add_f32_e32 v20, 1.0, v20
	v_rcp_f32_e32 v37, v20
	v_add_f32_e32 v20, 1.0, v32
	v_lshlrev_b32_e32 v32, 16, v21
	v_add_f32_e32 v38, 1.0, v33
	v_and_b32_e32 v33, 0xffff0000, v21
	v_mul_f32_e32 v21, 0xbfb8aa3b, v32
	v_exp_f32_e32 v39, v21
	v_mul_f32_e32 v21, 0xbfb8aa3b, v33
	v_exp_f32_e32 v40, v21
	v_rcp_f32_e32 v21, v38
	v_add_f32_e32 v38, 1.0, v39
	v_add_f32_e32 v36, 1.0, v36
	v_add_f32_e32 v39, 1.0, v40
	v_rcp_f32_e32 v20, v20
	v_rcp_f32_e32 v38, v38
	v_rcp_f32_e32 v39, v39
	v_rcp_f32_e32 v36, v36
	v_ashrrev_i32_e32 v19, 31, v18
	v_pk_mul_f32 v[20:21], v[22:23], v[20:21]
	v_pk_mul_f32 v[22:23], v[38:39], v[32:33]
	v_pk_mul_f32 v[34:35], v[36:37], v[34:35]
	v_pk_mul_f32 v[20:21], v[22:23], v[20:21]
	v_cvt_pk_bf16_f32 v23, v16, v17
	v_lshlrev_b64 v[16:17], 12, v[18:19]
	v_pk_mul_f32 v[30:31], v[34:35], v[30:31]
	v_lshl_add_u64 v[16:17], s[26:27], 0, v[16:17]
	v_cvt_pk_bf16_f32 v22, v28, v29
	v_lshl_add_u64 v[16:17], v[16:17], 0, v[46:47]
	v_cvt_pk_bf16_f32 v18, v30, v31
	v_cvt_pk_bf16_f32 v19, v20, v21
	v_add_u32_e32 v28, s36, v88
	global_store_dwordx2 v[16:17], v[22:23], off
	global_store_dwordx2 v[16:17], v[18:19], off offset:128
	v_mad_i64_i32 v[16:17], s[38:39], v28, s30, v[24:25]
	v_lshl_add_u64 v[16:17], v[16:17], 0, s[12:13]
	v_lshl_add_u64 v[30:31], v[16:17], 0, v[46:47]
	v_add_co_u32_e32 v16, vcc, s31, v30
	s_nop 1
	v_addc_co_u32_e32 v17, vcc, 0, v31, vcc
	global_load_dwordx2 v[32:33], v[16:17], off
	ds_read_b128 v[20:23], v89
	ds_read_b128 v[16:19], v89 offset:256
	v_lshl_add_u64 v[30:31], v[30:31], 0, s[18:19]
	s_waitcnt lgkmcnt(1)
	v_mov_b32_e32 v34, v20
	s_waitcnt lgkmcnt(0)
	v_mov_b32_e32 v35, v16
	v_mov_b32_e32 v36, v21
	v_mov_b32_e32 v37, v17
	v_pk_add_f32 v[34:35], v[34:35], v[36:37]
	v_mov_b32_e32 v36, v22
	v_mov_b32_e32 v37, v18
	v_mov_b32_e32 v38, v23
	v_mov_b32_e32 v39, v19
	v_pk_add_f32 v[36:37], v[36:37], v[38:39]
	global_load_dwordx2 v[38:39], v[30:31], off offset:128
	v_pk_add_f32 v[34:35], v[34:35], v[36:37]
	s_waitcnt vmcnt(1)
	v_lshlrev_b32_e32 v52, 16, v32
	v_add_f32_e32 v29, v34, v35
	s_nop 1
	v_mov_b32_dpp v34, v29 quad_perm:[1,0,3,2] row_mask:0xf bank_mask:0xf
	v_and_b32_e32 v53, 0xffff0000, v32
	v_mul_f32_e32 v32, 0xbfb8aa3b, v52
	v_exp_f32_e32 v32, v32
	v_lshlrev_b32_e32 v56, 16, v33
	s_waitcnt lgkmcnt(0)
	v_add_f32_e32 v29, v29, v34
	s_nop 1
	v_mov_b32_dpp v30, v29 quad_perm:[2,3,0,1] row_mask:0xf bank_mask:0xf
	v_and_b32_e32 v57, 0xffff0000, v33
	v_mul_f32_e32 v40, 0xbfb8aa3b, v56
	v_exp_f32_e32 v40, v40
	v_mul_f32_e32 v49, 0xbfb8aa3b, v57
	s_waitcnt lgkmcnt(0)
	v_add_f32_e32 v29, v29, v30
	s_nop 1
	v_mov_b32_dpp v30, v29 row_half_mirror row_mask:0xf bank_mask:0xf
	v_exp_f32_e32 v49, v49
	v_add_f32_e32 v40, 1.0, v40
	s_waitcnt lgkmcnt(0)
	v_add_f32_e32 v30, v29, v30
	s_nop 1
	v_mov_b32_dpp v31, v30 row_mirror row_mask:0xf bank_mask:0xf
	v_ashrrev_i32_e32 v29, 31, v28
	s_waitcnt lgkmcnt(0)
	v_add_f32_e32 v30, v30, v31
	v_fmamk_f32 v21, v30, 0xbc000000, v21
	v_fmamk_f32 v17, v30, 0xbc000000, v17
	v_fmamk_f32 v23, v30, 0xbc000000, v23
	v_fmamk_f32 v22, v30, 0xbc000000, v22
	v_fmac_f32_e32 v20, 0xbc000000, v30
	v_fmamk_f32 v51, v30, 0xbc000000, v19
	v_fmamk_f32 v50, v30, 0xbc000000, v18
	v_fmac_f32_e32 v16, 0xbc000000, v30
	v_mov_b32_e32 v30, v21
	v_mov_b32_e32 v31, v17
	v_mov_b32_e32 v18, v20
	v_mov_b32_e32 v19, v16
	v_pk_mul_f32 v[30:31], v[30:31], v[30:31]
	v_mov_b32_e32 v34, v23
	v_mov_b32_e32 v35, v51
	v_pk_fma_f32 v[18:19], v[18:19], v[18:19], v[30:31]
	v_mov_b32_e32 v30, v22
	v_mov_b32_e32 v31, v50
	v_pk_mul_f32 v[34:35], v[34:35], v[34:35]
	s_nop 0
	v_pk_fma_f32 v[30:31], v[30:31], v[30:31], v[34:35]
	v_mul_f32_e32 v34, 0xbfb8aa3b, v53
	v_exp_f32_e32 v34, v34
	v_pk_add_f32 v[18:19], v[18:19], v[30:31]
	v_add_f32_e32 v30, 1.0, v32
	v_rcp_f32_e32 v54, v30
	v_add_f32_e32 v30, 1.0, v34
	v_rcp_f32_e32 v55, v30
	ds_read_b128 v[30:33], v91
	ds_read_b128 v[34:37], v91 offset:256
	v_pk_mul_f32 v[52:53], v[54:55], v[52:53]
	s_waitcnt lgkmcnt(1)
	v_mov_b32_e32 v58, v30
	s_waitcnt lgkmcnt(0)
	v_mov_b32_e32 v59, v34
	v_mov_b32_e32 v60, v31
	v_mov_b32_e32 v61, v35
	v_pk_add_f32 v[58:59], v[58:59], v[60:61]
	v_mov_b32_e32 v60, v32
	v_mov_b32_e32 v61, v36
	v_mov_b32_e32 v62, v33
	v_mov_b32_e32 v63, v37
	v_pk_add_f32 v[60:61], v[60:61], v[62:63]
	s_nop 0
	v_pk_add_f32 v[58:59], v[58:59], v[60:61]
	s_nop 0
	v_add_f32_e32 v60, v58, v59
	s_nop 1
	v_mov_b32_dpp v61, v60 quad_perm:[1,0,3,2] row_mask:0xf bank_mask:0xf
	v_rcp_f32_e32 v58, v40
	v_add_f32_e32 v40, 1.0, v49
	v_rcp_f32_e32 v59, v40
	s_waitcnt lgkmcnt(0)
	v_add_f32_e32 v40, v60, v61
	s_nop 1
	v_mov_b32_dpp v49, v40 quad_perm:[2,3,0,1] row_mask:0xf bank_mask:0xf
	s_waitcnt vmcnt(0)
	v_lshlrev_b32_e32 v60, 16, v38
	v_mul_f32_e32 v61, 0xbfb8aa3b, v60
	v_exp_f32_e32 v62, v61
	v_and_b32_e32 v61, 0xffff0000, v38
	s_waitcnt lgkmcnt(0)
	v_add_f32_e32 v38, v40, v49
	s_nop 1
	v_mov_b32_dpp v40, v38 row_half_mirror row_mask:0xf bank_mask:0xf
	v_add_f32_e32 v49, 1.0, v62
	v_mul_f32_e32 v62, 0xbfb8aa3b, v61
	v_exp_f32_e32 v63, v62
	v_rcp_f32_e32 v62, v49
	s_waitcnt lgkmcnt(0)
	v_add_f32_e32 v40, v38, v40
	s_nop 1
	v_mov_b32_dpp v49, v40 row_mirror row_mask:0xf bank_mask:0xf
	v_add_f32_e32 v38, 1.0, v63
	v_rcp_f32_e32 v63, v38
	v_pk_mul_f32 v[54:55], v[58:59], v[56:57]
	v_lshlrev_b32_e32 v38, 16, v39
	s_waitcnt lgkmcnt(0)
; DI float siluf_(float x) { return x * frcp(1.f + fexp(-x)); }
; DI float dot4(const f32x4 a) { return (a[0] * a[0] + a[1] * a[1]) + (a[2] * a[2] + a[3] * a[3]); }
; DI void conv_item(LAS unsigned char* lds, int item, const bf16_t* P, const float* cw, const float* cb, const float* lng, const float* lnb, bf16_t* MIX) {
;     ...
;             sm += __shfl_xor(sm, 1); sm += __shfl_xor(sm, 2); sm += __shfl_xor(sm, 4); sm += __shfl_xor(sm, 8);
;             const float mu = sm * (1.f / 128.f);
;             va = va - mu; vb = vb - mu;
;             float sq = dot4(va) + dot4(vb);
;             sq += __shfl_xor(sq, 1); sq += __shfl_xor(sq, 2); sq += __shfl_xor(sq, 4); sq += __shfl_xor(sq, 8);
;             const float rstd = rsqrtf(sq * (1.f / 128.f) + EPS_);
;             f32x4 oa = va * rstd * ga + ba, ob = vb * rstd * gb + bb;
;             oa[0] = siluf_(oa[0]) * siluf_(bflo(za.x)); oa[1] = siluf_(oa[1]) * siluf_(bfhi(za.x)); oa[2] = siluf_(oa[2]) * siluf_(bflo(za.y)); oa[3] = siluf_(oa[3]) * siluf_(bfhi(za.y));
;             ob[0] = siluf_(ob[0]) * siluf_(bflo(zb.x)); ob[1] = siluf_(ob[1]) * siluf_(bfhi(zb.x)); ob[2] = siluf_(ob[2]) * siluf_(bflo(zb.y)); ob[3] = siluf_(ob[3]) * siluf_(bfhi(zb.y));
	v_add_f32_e32 v40, v40, v49
	v_fmamk_f32 v31, v40, 0xbc000000, v31
	v_fmamk_f32 v35, v40, 0xbc000000, v35
	v_fmamk_f32 v33, v40, 0xbc000000, v33
	v_fmac_f32_e32 v30, 0xbc000000, v40
	v_fmamk_f32 v37, v40, 0xbc000000, v37
	v_fmac_f32_e32 v34, 0xbc000000, v40
	v_mov_b32_e32 v66, v31
	v_mov_b32_e32 v67, v35
	v_fmamk_f32 v32, v40, 0xbc000000, v32
	v_fmamk_f32 v36, v40, 0xbc000000, v36
	v_mov_b32_e32 v64, v30
	v_mov_b32_e32 v65, v34
	v_pk_mul_f32 v[66:67], v[66:67], v[66:67]
	v_mov_b32_e32 v92, v33
	v_mov_b32_e32 v93, v37
	v_pk_fma_f32 v[64:65], v[64:65], v[64:65], v[66:67]
	v_mov_b32_e32 v66, v32
	v_mov_b32_e32 v67, v36
	v_pk_mul_f32 v[92:93], v[92:93], v[92:93]
	v_pk_mul_f32 v[56:57], v[62:63], v[60:61]
	v_pk_fma_f32 v[66:67], v[66:67], v[66:67], v[92:93]
	v_and_b32_e32 v39, 0xffff0000, v39
	v_pk_add_f32 v[64:65], v[64:65], v[66:67]
	v_mov_b32_e32 v67, v18
	v_mov_b32_e32 v66, v64
	v_mov_b32_e32 v18, v65
	v_pk_add_f32 v[18:19], v[66:67], v[18:19]
	s_nop 1
	v_mov_b32_dpp v65, v19 quad_perm:[1,0,3,2] row_mask:0xf bank_mask:0xf
	s_nop 1
	v_mov_b32_dpp v64, v18 quad_perm:[1,0,3,2] row_mask:0xf bank_mask:0xf
	v_mul_f32_e32 v40, 0xbfb8aa3b, v38
	v_exp_f32_e32 v40, v40
	v_mul_f32_e32 v49, 0xbfb8aa3b, v39
	v_exp_f32_e32 v49, v49
	s_waitcnt lgkmcnt(0)
	v_pk_add_f32 v[18:19], v[18:19], v[64:65]
	s_nop 1
	v_mov_b32_dpp v65, v19 quad_perm:[2,3,0,1] row_mask:0xf bank_mask:0xf
	s_nop 1
	v_mov_b32_dpp v64, v18 quad_perm:[2,3,0,1] row_mask:0xf bank_mask:0xf
	v_add_f32_e32 v40, 1.0, v40
	v_rcp_f32_e32 v66, v40
	v_add_f32_e32 v40, 1.0, v49
	v_rcp_f32_e32 v67, v40
	s_waitcnt lgkmcnt(0)
	v_pk_add_f32 v[18:19], v[18:19], v[64:65]
	s_nop 1
	v_mov_b32_dpp v65, v19 row_half_mirror row_mask:0xf bank_mask:0xf
	s_nop 1
	v_mov_b32_dpp v64, v18 row_half_mirror row_mask:0xf bank_mask:0xf
	v_pk_mul_f32 v[38:39], v[66:67], v[38:39]
	s_waitcnt lgkmcnt(0)
	v_pk_add_f32 v[58:59], v[18:19], v[64:65]
	s_nop 1
	v_mov_b32_dpp v61, v59 row_mirror row_mask:0xf bank_mask:0xf
	s_nop 1
	v_mov_b32_dpp v60, v58 row_mirror row_mask:0xf bank_mask:0xf
	v_lshlrev_b64 v[18:19], 12, v[28:29]
	v_lshl_add_u64 v[18:19], s[26:27], 0, v[18:19]
	v_lshl_add_u64 v[28:29], v[18:19], 0, v[46:47]
	v_add_u32_e32 v18, s36, v90
	s_waitcnt lgkmcnt(0)
	v_pk_add_f32 v[58:59], v[58:59], v[60:61]
	v_mad_i64_i32 v[24:25], s[36:37], v18, s30, v[24:25]
	v_pk_fma_f32 v[26:27], v[58:59], s[20:21], v[26:27] op_sel_hi:[1,0,0]
	v_lshl_add_u64 v[24:25], v[24:25], 0, s[12:13]
	v_mul_f32_e32 v19, 0x4b800000, v27
	v_cmp_gt_f32_e32 vcc, s34, v27
	v_lshl_add_u64 v[24:25], v[24:25], 0, v[46:47]
	s_add_i32 s21, s21, s23
	v_cndmask_b32_e32 v19, v27, v19, vcc
	v_rsq_f32_e32 v19, v19
	s_cmpk_gt_i32 s35, 0x1ff
	v_mul_f32_e32 v27, 0x45800000, v19
	v_cndmask_b32_e32 v40, v19, v27, vcc
	v_pk_mul_f32 v[20:21], v[20:21], v[40:41] op_sel_hi:[1,0]
	v_pk_mul_f32 v[22:23], v[22:23], v[40:41] op_sel_hi:[1,0]
	v_pk_fma_f32 v[20:21], v[8:9], v[20:21], v[12:13]
	v_pk_fma_f32 v[22:23], v[10:11], v[22:23], v[14:15]
	v_mul_f32_e32 v19, 0xbfb8aa3b, v20
	v_exp_f32_e32 v19, v19
	v_mul_f32_e32 v27, 0xbfb8aa3b, v21
	v_exp_f32_e32 v27, v27
	v_pk_mul_f32 v[16:17], v[16:17], v[40:41] op_sel_hi:[1,0]
	v_add_f32_e32 v19, 1.0, v19
	v_rcp_f32_e32 v58, v19
	v_add_f32_e32 v19, 1.0, v27
	v_rcp_f32_e32 v59, v19
	v_mul_f32_e32 v19, 0xbfb8aa3b, v22
	v_exp_f32_e32 v19, v19
	v_mul_f32_e32 v27, 0xbfb8aa3b, v23
	v_exp_f32_e32 v27, v27
	v_pk_mul_f32 v[20:21], v[20:21], v[58:59]
	v_add_f32_e32 v19, 1.0, v19
	v_pk_fma_f32 v[16:17], v[0:1], v[16:17], v[4:5]
	v_pk_mul_f32 v[20:21], v[52:53], v[20:21]
	v_rcp_f32_e32 v52, v19
	v_add_f32_e32 v19, 1.0, v27
	v_rcp_f32_e32 v53, v19
	v_mul_f32_e32 v19, 0xbfb8aa3b, v16
	v_exp_f32_e32 v19, v19
	v_mul_f32_e32 v27, 0xbfb8aa3b, v17
	v_exp_f32_e32 v27, v27
	v_pk_mul_f32 v[50:51], v[50:51], v[40:41] op_sel_hi:[1,0]
	v_add_f32_e32 v19, 1.0, v19
	v_pk_fma_f32 v[50:51], v[2:3], v[50:51], v[6:7]
	v_pk_mul_f32 v[22:23], v[22:23], v[52:53]
	v_rcp_f32_e32 v52, v19
	v_add_f32_e32 v19, 1.0, v27
	v_mul_f32_e32 v27, 0xbfb8aa3b, v50
	v_exp_f32_e32 v27, v27
	v_mul_f32_e32 v40, 0xbfb8aa3b, v51
	v_exp_f32_e32 v40, v40
	v_rcp_f32_e32 v53, v19
	v_add_f32_e32 v19, 1.0, v27
	v_rcp_f32_e32 v58, v19
	v_add_f32_e32 v19, 1.0, v40
	v_rcp_f32_e32 v59, v19
	v_pk_mul_f32 v[16:17], v[16:17], v[52:53]
	v_pk_mul_f32 v[22:23], v[54:55], v[22:23]
	v_pk_mul_f32 v[16:17], v[56:57], v[16:17]
	v_pk_mul_f32 v[50:51], v[50:51], v[58:59]
	v_cvt_pk_bf16_f32 v16, v16, v17
	v_pk_mul_f32 v[38:39], v[38:39], v[50:51]
	v_cvt_pk_bf16_f32 v20, v20, v21
	v_cvt_pk_bf16_f32 v17, v38, v39
	v_cvt_pk_bf16_f32 v21, v22, v23
	global_store_dwordx2 v[28:29], v[16:17], off offset:128
	v_add_co_u32_e32 v16, vcc, s31, v24
	global_store_dwordx2 v[28:29], v[20:21], off
	s_nop 0
	v_addc_co_u32_e32 v17, vcc, 0, v25, vcc
	global_load_dwordx2 v[16:17], v[16:17], off
	v_lshl_add_u64 v[20:21], v[24:25], 0, s[18:19]
	global_load_dwordx2 v[20:21], v[20:21], off offset:128
	v_mul_f32_e32 v19, 0x4b800000, v26
	v_cmp_gt_f32_e32 vcc, s34, v26
	s_nop 1
	v_cndmask_b32_e32 v19, v26, v19, vcc
	v_rsq_f32_e32 v22, v19
	v_ashrrev_i32_e32 v19, 31, v18
	v_mul_f32_e32 v23, 0x45800000, v22
	v_cndmask_b32_e32 v22, v22, v23, vcc
	v_pk_mul_f32 v[24:25], v[30:31], v[22:23] op_sel_hi:[1,0]
	v_pk_mul_f32 v[26:27], v[32:33], v[22:23] op_sel_hi:[1,0]
	v_pk_fma_f32 v[8:9], v[8:9], v[24:25], v[12:13]
	v_pk_fma_f32 v[10:11], v[10:11], v[26:27], v[14:15]
	v_pk_mul_f32 v[14:15], v[36:37], v[22:23] op_sel_hi:[1,0]
	v_pk_mul_f32 v[12:13], v[34:35], v[22:23] op_sel_hi:[1,0]
	v_pk_fma_f32 v[2:3], v[2:3], v[14:15], v[6:7]
	v_mul_f32_e32 v6, 0xbfb8aa3b, v8
	v_exp_f32_e32 v6, v6
	v_mul_f32_e32 v7, 0xbfb8aa3b, v9
	v_exp_f32_e32 v7, v7
	v_pk_fma_f32 v[0:1], v[0:1], v[12:13], v[4:5]
	v_add_f32_e32 v4, 1.0, v6
	v_rcp_f32_e32 v4, v4
	v_add_f32_e32 v5, 1.0, v7
	v_rcp_f32_e32 v5, v5
	s_waitcnt vmcnt(1)
; DI float siluf_(float x) { return x * frcp(1.f + fexp(-x)); }
; DI u32x2 pack4(const f32x4 a) { u32x2 w; w.x = pk2(a[0], a[1]); w.y = pk2(a[2], a[3]); return w; }
; DI void conv_item(LAS unsigned char* lds, int item, const bf16_t* P, const float* cw, const float* cb, const float* lng, const float* lnb, bf16_t* MIX) {
;     ...
;             f32x4 oa = va * rstd * ga + ba, ob = vb * rstd * gb + bb;
;             oa[0] = siluf_(oa[0]) * siluf_(bflo(za.x)); oa[1] = siluf_(oa[1]) * siluf_(bfhi(za.x)); oa[2] = siluf_(oa[2]) * siluf_(bflo(za.y)); oa[3] = siluf_(oa[3]) * siluf_(bfhi(za.y));
;             ob[0] = siluf_(ob[0]) * siluf_(bflo(zb.x)); ob[1] = siluf_(ob[1]) * siluf_(bfhi(zb.x)); ob[2] = siluf_(ob[2]) * siluf_(bflo(zb.y)); ob[3] = siluf_(ob[3]) * siluf_(bfhi(zb.y));
;             *(u32x2*)(MIX + row * DM + cbase + ca) = pack4(oa); *(u32x2*)(MIX + row * DM + cbase + cb2) = pack4(ob);
;         }
;     }
	v_lshlrev_b32_e32 v6, 16, v16
	v_mul_f32_e32 v7, 0xbfb8aa3b, v6
	v_exp_f32_e32 v12, v7
	v_and_b32_e32 v7, 0xffff0000, v16
	v_mul_f32_e32 v13, 0xbfb8aa3b, v7
	v_exp_f32_e32 v13, v13
	v_pk_mul_f32 v[4:5], v[8:9], v[4:5]
	v_mul_f32_e32 v9, 0xbfb8aa3b, v10
	v_exp_f32_e32 v9, v9
	v_add_f32_e32 v8, 1.0, v13
	v_mul_f32_e32 v13, 0xbfb8aa3b, v11
	v_exp_f32_e32 v14, v13
	v_rcp_f32_e32 v13, v8
	v_add_f32_e32 v8, 1.0, v9
	v_and_b32_e32 v15, 0xffff0000, v17
	v_add_f32_e32 v9, 1.0, v14
	v_lshlrev_b32_e32 v14, 16, v17
	v_add_f32_e32 v12, 1.0, v12
	v_mul_f32_e32 v16, 0xbfb8aa3b, v14
	v_mul_f32_e32 v17, 0xbfb8aa3b, v15
	v_rcp_f32_e32 v12, v12
	v_exp_f32_e32 v16, v16
	v_exp_f32_e32 v17, v17
	v_rcp_f32_e32 v8, v8
	v_rcp_f32_e32 v9, v9
	v_add_f32_e32 v16, 1.0, v16
	v_add_f32_e32 v17, 1.0, v17
	v_pk_mul_f32 v[6:7], v[12:13], v[6:7]
	v_rcp_f32_e32 v16, v16
	v_rcp_f32_e32 v17, v17
	v_pk_mul_f32 v[4:5], v[6:7], v[4:5]
	v_pk_mul_f32 v[6:7], v[10:11], v[8:9]
	v_mul_f32_e32 v10, 0xbfb8aa3b, v0
	v_exp_f32_e32 v10, v10
	v_mul_f32_e32 v11, 0xbfb8aa3b, v1
	v_exp_f32_e32 v11, v11
	v_pk_mul_f32 v[8:9], v[16:17], v[14:15]
	s_waitcnt vmcnt(0)
	v_and_b32_e32 v15, 0xffff0000, v21
	v_pk_mul_f32 v[6:7], v[8:9], v[6:7]
	v_add_f32_e32 v8, 1.0, v10
	v_lshlrev_b32_e32 v10, 16, v20
	v_add_f32_e32 v9, 1.0, v11
	v_mul_f32_e32 v11, 0xbfb8aa3b, v10
	v_exp_f32_e32 v12, v11
	v_and_b32_e32 v11, 0xffff0000, v20
	v_mul_f32_e32 v13, 0xbfb8aa3b, v11
	v_rcp_f32_e32 v8, v8
	v_rcp_f32_e32 v9, v9
	v_exp_f32_e32 v13, v13
	v_mul_f32_e32 v17, 0xbfb8aa3b, v15
	v_exp_f32_e32 v17, v17
	v_pk_mul_f32 v[0:1], v[0:1], v[8:9]
	v_add_f32_e32 v8, 1.0, v13
	v_mul_f32_e32 v9, 0xbfb8aa3b, v2
	v_mul_f32_e32 v13, 0xbfb8aa3b, v3
	v_exp_f32_e32 v9, v9
	v_exp_f32_e32 v14, v13
	v_rcp_f32_e32 v13, v8
	v_add_f32_e32 v12, 1.0, v12
	v_add_f32_e32 v8, 1.0, v9
	v_add_f32_e32 v9, 1.0, v14
	v_lshlrev_b32_e32 v14, 16, v21
	v_mul_f32_e32 v16, 0xbfb8aa3b, v14
	v_exp_f32_e32 v16, v16
	v_add_f32_e32 v17, 1.0, v17
	v_rcp_f32_e32 v12, v12
	v_rcp_f32_e32 v8, v8
	v_add_f32_e32 v16, 1.0, v16
	v_rcp_f32_e32 v9, v9
	v_rcp_f32_e32 v16, v16
	v_rcp_f32_e32 v17, v17
	v_pk_mul_f32 v[10:11], v[12:13], v[10:11]
	v_pk_mul_f32 v[2:3], v[2:3], v[8:9]
	v_cvt_pk_bf16_f32 v4, v4, v5
	v_pk_mul_f32 v[8:9], v[16:17], v[14:15]
	v_cvt_pk_bf16_f32 v5, v6, v7
	v_lshlrev_b64 v[6:7], 12, v[18:19]
	v_pk_mul_f32 v[0:1], v[10:11], v[0:1]
	v_pk_mul_f32 v[2:3], v[8:9], v[2:3]
	v_lshl_add_u64 v[6:7], s[26:27], 0, v[6:7]
	v_lshl_add_u64 v[6:7], v[6:7], 0, v[46:47]
	v_cvt_pk_bf16_f32 v0, v0, v1
	v_cvt_pk_bf16_f32 v1, v2, v3
	global_store_dwordx2 v[6:7], v[4:5], off
	global_store_dwordx2 v[6:7], v[0:1], off offset:128
	s_barrier
	s_cbranch_scc1 .LBB0_532
